# wave reductions in norm/mix phases: ds_bpermute butterfly hops replaced by permlane32/16_swap + DPP row_ror moves (bit-identical)
# speedup vs baseline: 1.0424x; 1.0031x over previous
; DI float lo_bf(unsigned u) { return __uint_as_float(u << 16); }
; DI float hi_bf(unsigned u) { return __uint_as_float(u & 0xffff0000u); }
; DI void phase_mix_gla(const Params& p, int j, int row_lo, int nrows, int bid, int nb) {
;     ...
;             const u32x4 gq0 = *(const u32x4*)(row + 6144 + c0), gq1 = *(const u32x4*)(row + 6144 + c0 + 8);
; #pragma unroll
;             for (int q = 0; q < 2; ++q) { const u32x4 a = *(const u32x4*)(row + c0 + 8 * q), b = *(const u32x4*)(row + 2048 + c0 + 8 * q);
;                 o[8 * q + 0] = lo_bf(a.x) + lo_bf(b.x); o[8 * q + 1] = hi_bf(a.x) + hi_bf(b.x); o[8 * q + 2] = lo_bf(a.y) + lo_bf(b.y); o[8 * q + 3] = hi_bf(a.y) + hi_bf(b.y);
;                 o[8 * q + 4] = lo_bf(a.z) + lo_bf(b.z); o[8 * q + 5] = hi_bf(a.z) + hi_bf(b.z); o[8 * q + 6] = lo_bf(a.w) + lo_bf(b.w); o[8 * q + 7] = hi_bf(a.w) + hi_bf(b.w); }
;             float ss = 0.f;
; #pragma unroll
;             for (int i = 0; i < 16; ++i) ss += o[i] * o[i];
; #pragma unroll
;             for (int m = 8; m > 0; m >>= 1) ss += __shfl_xor(ss, m);
;             const float rs = rsqrtf(ss * (1.f / 256.f) + LN_EPS);
.LBB0_742:
	v_lshl_add_u64 v[2:3], v[28:29], 0, s[24:25]
	global_load_dwordx4 v[22:25], v[28:29], off offset:-16
	global_load_dwordx4 v[14:17], v[2:3], off offset:16
	v_lshl_add_u64 v[2:3], v[28:29], 0, s[26:27]
	global_load_dwordx4 v[18:21], v[2:3], off offset:16
	v_add_co_u32_e32 v2, vcc, 0xffffd000, v28
	v_add_u32_e32 v1, s28, v1
	s_nop 0
	v_addc_co_u32_e32 v3, vcc, -1, v29, vcc
	global_load_dwordx4 v[56:59], v[2:3], off offset:-16
	v_add_co_u32_e32 v30, vcc, 0xffffe000, v28
	s_waitcnt vmcnt(3)
	v_lshlrev_b32_e32 v55, 16, v24
	v_addc_co_u32_e32 v31, vcc, -1, v29, vcc
	global_load_dwordx4 v[60:63], v[30:31], off offset:-16
	global_load_dwordx4 v[2:5], v[28:29], off
	global_load_dwordx4 v[6:9], v[26:27], off offset:16
	global_load_dwordx4 v[10:13], v[26:27], off
	v_and_b32_e32 v24, 0xffff0000, v24
	s_waitcnt vmcnt(6)
	v_and_b32_e32 v30, 0xffff0000, v17
	v_lshlrev_b32_e32 v31, 16, v17
	s_waitcnt vmcnt(5)
	v_and_b32_e32 v32, 0xffff0000, v21
	v_lshlrev_b32_e32 v33, 16, v21
	v_mul_f32_e32 v17, 0xbfb8aa3b, v55
	v_mul_f32_e32 v21, 0xbfb8aa3b, v24
	v_lshlrev_b32_e32 v64, 16, v23
	v_and_b32_e32 v23, 0xffff0000, v23
	v_exp_f32_e32 v40, v17
	v_exp_f32_e32 v41, v21
	v_mul_f32_e32 v38, 0xbfb8aa3b, v64
	v_mul_f32_e32 v39, 0xbfb8aa3b, v23
	v_exp_f32_e32 v48, v38
	v_exp_f32_e32 v49, v39
	v_pk_add_f32 v[40:41], v[40:41], 1.0 op_sel_hi:[1,0]
	s_waitcnt vmcnt(4)
	v_lshlrev_b32_e32 v36, 16, v57
	v_div_scale_f32 v17, s[4:5], v41, v41, v24
	v_and_b32_e32 v37, 0xffff0000, v57
	v_pk_add_f32 v[48:49], v[48:49], 1.0 op_sel_hi:[1,0]
	v_div_scale_f32 v57, s[4:5], v40, v40, v55
	v_pk_add_f32 v[30:31], v[30:31], v[32:33]
	v_lshlrev_b32_e32 v32, 16, v59
	v_and_b32_e32 v33, 0xffff0000, v59
	v_div_scale_f32 v59, s[6:7], v49, v49, v23
	v_rcp_f32_e32 v65, v57
	v_rcp_f32_e32 v66, v59
	v_div_scale_f32 v21, vcc, v24, v41, v24
	v_fma_f32 v69, -v57, v65, 1.0
	v_lshlrev_b32_e32 v34, 16, v58
	v_and_b32_e32 v35, 0xffff0000, v58
	v_div_scale_f32 v58, s[4:5], v55, v40, v55
	v_fma_f32 v70, -v59, v66, 1.0
	v_fmac_f32_e32 v65, v69, v65
	v_fmac_f32_e32 v66, v70, v66
	v_mul_f32_e32 v69, v58, v65
	v_fma_f32 v72, -v57, v69, v58
	v_fmac_f32_e32 v69, v72, v65
	v_pk_mul_f32 v[38:39], v[30:31], v[30:31]
	s_waitcnt vmcnt(3)
	v_lshlrev_b32_e32 v42, 16, v63
	v_and_b32_e32 v43, 0xffff0000, v63
	v_rcp_f32_e32 v63, v17
	v_lshlrev_b32_e32 v46, 16, v61
	v_and_b32_e32 v47, 0xffff0000, v61
	v_div_scale_f32 v61, s[6:7], v23, v49, v23
	v_fma_f32 v68, -v17, v63, 1.0
	v_fmac_f32_e32 v63, v68, v63
	v_mul_f32_e32 v68, v21, v63
	v_fma_f32 v71, -v17, v68, v21
	v_lshlrev_b32_e32 v44, 16, v62
	v_and_b32_e32 v45, 0xffff0000, v62
	v_div_scale_f32 v62, s[34:35], v48, v48, v64
	v_mul_f32_e32 v70, v61, v66
	v_fmac_f32_e32 v68, v71, v63
	v_rcp_f32_e32 v67, v62
	v_fma_f32 v73, -v59, v70, v61
	v_fma_f32 v17, -v17, v68, v21
	v_fmac_f32_e32 v70, v73, v66
	v_fma_f32 v21, -v57, v69, v58
	v_div_fmas_f32 v17, v17, v63, v68
	s_mov_b64 vcc, s[4:5]
	v_fma_f32 v57, -v59, v70, v61
	v_div_fixup_f32 v41, v17, v41, v24
	v_div_fmas_f32 v17, v21, v65, v69
	s_mov_b64 vcc, s[6:7]
	v_div_fixup_f32 v40, v17, v40, v55
	v_div_fmas_f32 v17, v57, v66, v70
	v_div_fixup_f32 v49, v17, v49, v23
	v_fma_f32 v17, -v62, v67, 1.0
	v_fmac_f32_e32 v67, v17, v67
	v_div_scale_f32 v17, vcc, v64, v48, v64
	v_mul_f32_e32 v21, v17, v67
	v_fma_f32 v23, -v62, v21, v17
	v_fmac_f32_e32 v21, v23, v67
	v_fma_f32 v17, -v62, v21, v17
	v_div_fmas_f32 v17, v17, v67, v21
	v_div_fixup_f32 v48, v17, v48, v64
	v_lshlrev_b32_e32 v17, 16, v22
	v_and_b32_e32 v21, 0xffff0000, v22
	v_mul_f32_e32 v22, 0xbfb8aa3b, v17
	v_mul_f32_e32 v23, 0xbfb8aa3b, v21
	v_exp_f32_e32 v22, v22
	v_exp_f32_e32 v23, v23
	v_lshlrev_b32_e32 v58, 16, v56
	v_and_b32_e32 v59, 0xffff0000, v56
	v_lshlrev_b32_e32 v56, 16, v60
	v_pk_add_f32 v[22:23], v[22:23], 1.0 op_sel_hi:[1,0]
	v_and_b32_e32 v57, 0xffff0000, v60
	v_div_scale_f32 v24, s[4:5], v23, v23, v21
	v_rcp_f32_e32 v55, v24
	v_lshlrev_b32_e32 v66, 16, v25
	v_and_b32_e32 v67, 0xffff0000, v25
	v_mul_f32_e32 v25, 0xbfb8aa3b, v67
	v_fma_f32 v60, -v24, v55, 1.0
	v_fmac_f32_e32 v55, v60, v55
	v_div_scale_f32 v60, vcc, v21, v23, v21
	v_mul_f32_e32 v61, v60, v55
	v_fma_f32 v62, -v24, v61, v60
	v_fmac_f32_e32 v61, v62, v55
	v_fma_f32 v24, -v24, v61, v60
	v_div_scale_f32 v60, s[4:5], v22, v22, v17
	v_div_fmas_f32 v24, v24, v55, v61
	v_rcp_f32_e32 v62, v60
	v_div_fixup_f32 v23, v24, v23, v21
	v_mul_f32_e32 v24, 0xbfb8aa3b, v66
	v_exp_f32_e32 v24, v24
	v_exp_f32_e32 v25, v25
	v_fma_f32 v21, -v60, v62, 1.0
	v_fmac_f32_e32 v62, v21, v62
	v_div_scale_f32 v21, vcc, v17, v22, v17
	v_pk_add_f32 v[24:25], v[24:25], 1.0 op_sel_hi:[1,0]
	v_mul_f32_e32 v55, v21, v62
	v_div_scale_f32 v68, s[4:5], v25, v25, v67
	v_pk_add_f32 v[56:57], v[58:59], v[56:57]
	v_fma_f32 v61, -v60, v55, v21
	v_rcp_f32_e32 v69, v68
	v_pk_add_f32 v[36:37], v[36:37], v[46:47]
	v_pk_mul_f32 v[58:59], v[56:57], v[56:57]
	v_fmac_f32_e32 v55, v61, v62
	v_pk_mul_f32 v[46:47], v[36:37], v[36:37]
	v_fma_f32 v21, -v60, v55, v21
	v_add_f32_e32 v58, v58, v59
	v_pk_add_f32 v[34:35], v[34:35], v[44:45]
	v_div_fmas_f32 v21, v21, v62, v55
	v_add_f32_e32 v46, v46, v58
	v_pk_mul_f32 v[44:45], v[34:35], v[34:35]
	v_div_fixup_f32 v22, v21, v22, v17
	v_fma_f32 v17, -v68, v69, 1.0
	v_add_f32_e32 v46, v47, v46
	v_pk_add_f32 v[32:33], v[32:33], v[42:43]
	v_fmac_f32_e32 v69, v17, v69
	v_lshlrev_b32_e32 v60, 16, v16
	v_and_b32_e32 v61, 0xffff0000, v16
	v_lshlrev_b32_e32 v16, 16, v20
	v_and_b32_e32 v17, 0xffff0000, v20
	v_add_f32_e32 v44, v44, v46
	v_pk_mul_f32 v[42:43], v[32:33], v[32:33]
	v_pk_add_f32 v[16:17], v[60:61], v[16:17]
	v_lshlrev_b32_e32 v60, 16, v15
	v_and_b32_e32 v61, 0xffff0000, v15
	v_lshlrev_b32_e32 v64, 16, v14
	v_and_b32_e32 v65, 0xffff0000, v14
	v_lshlrev_b32_e32 v14, 16, v18
	v_and_b32_e32 v15, 0xffff0000, v18
	v_add_f32_e32 v44, v45, v44
	v_pk_add_f32 v[14:15], v[64:65], v[14:15]
	v_add_f32_e32 v42, v42, v44
	v_lshlrev_b32_e32 v62, 16, v19
	v_and_b32_e32 v63, 0xffff0000, v19
	v_pk_mul_f32 v[18:19], v[14:15], v[14:15]
	v_add_f32_e32 v42, v43, v42
	v_pk_add_f32 v[60:61], v[60:61], v[62:63]
	v_add_f32_e32 v18, v18, v42
	v_pk_mul_f32 v[62:63], v[60:61], v[60:61]
	v_add_f32_e32 v18, v19, v18
	v_add_f32_e32 v18, v62, v18
	v_pk_mul_f32 v[20:21], v[16:17], v[16:17]
	v_add_f32_e32 v18, v63, v18
	v_add_f32_e32 v18, v20, v18
	v_add_f32_e32 v18, v21, v18
	v_add_f32_e32 v18, v39, v18
	v_add_f32_e32 v18, v38, v18
	s_nop 1
	v_mov_b32_dpp v19, v18 row_ror:8 row_mask:0xf bank_mask:0xf
	v_div_scale_f32 v55, vcc, v67, v25, v67
	v_mul_f32_e32 v70, v55, v69
	v_fma_f32 v71, -v68, v70, v55
	s_waitcnt lgkmcnt(0)
; DI unsigned pk2(float lo, float hi) { f32x2 v = {lo, hi}; bfv2 b = __builtin_convertvector(v, bfv2); return __builtin_bit_cast(unsigned, b); }
; DI float lo_bf(unsigned u) { return __uint_as_float(u << 16); }
; DI float hi_bf(unsigned u) { return __uint_as_float(u & 0xffff0000u); }
; DI float silu(float x) { return x / (1.f + __expf(-x)); }
; DI void phase_mix_gla(const Params& p, int j, int row_lo, int nrows, int bid, int nb) {
;     ...
;             for (int m = 8; m > 0; m >>= 1) ss += __shfl_xor(ss, m);
;             const float rs = rsqrtf(ss * (1.f / 256.f) + LN_EPS);
;             const int vc = (lane & 15) * 16;
; #pragma unroll
;             for (int q = 0; q < 2; ++q) { const u32x4 gq = q ? gq1 : gq0;
;                 const f32x4 w0 = *(const f32x4*)(gnw + vc + 8 * q), w1 = *(const f32x4*)(gnw + vc + 8 * q + 4);
;                 u32x4 y;
;                 y.x = pk2(o[8 * q + 0] * rs * w0[0] * silu(lo_bf(gq.x)), o[8 * q + 1] * rs * w0[1] * silu(hi_bf(gq.x)));
;                 y.y = pk2(o[8 * q + 2] * rs * w0[2] * silu(lo_bf(gq.y)), o[8 * q + 3] * rs * w0[3] * silu(hi_bf(gq.y)));
;                 y.z = pk2(o[8 * q + 4] * rs * w1[0] * silu(lo_bf(gq.z)), o[8 * q + 5] * rs * w1[1] * silu(hi_bf(gq.z)));
;                 y.w = pk2(o[8 * q + 6] * rs * w1[2] * silu(lo_bf(gq.w)), o[8 * q + 7] * rs * w1[3] * silu(hi_bf(gq.w)));
;                 *(u32x4*)(row + 6144 + c0 + 8 * q) = y; }
	v_add_f32_e32 v18, v18, v19
	s_nop 1
	v_mov_b32_dpp v21, v18 row_ror:4 row_mask:0xf bank_mask:0xf
	v_fmac_f32_e32 v70, v71, v69
	v_fma_f32 v20, -v68, v70, v55
	v_div_fmas_f32 v20, v20, v69, v70
	v_div_fixup_f32 v19, v20, v25, v67
	s_waitcnt lgkmcnt(0)
	v_add_f32_e32 v18, v18, v21
	s_nop 1
	v_mov_b32_dpp v20, v18 row_ror:2 row_mask:0xf bank_mask:0xf
	v_div_scale_f32 v38, s[4:5], v24, v24, v66
	v_rcp_f32_e32 v39, v38
	s_waitcnt lgkmcnt(0)
	v_add_f32_e32 v18, v18, v20
	s_nop 1
	v_mov_b32_dpp v20, v18 row_ror:1 row_mask:0xf bank_mask:0xf
	v_fma_f32 v21, -v38, v39, 1.0
	v_fmac_f32_e32 v39, v21, v39
	v_div_scale_f32 v21, vcc, v66, v24, v66
	s_waitcnt lgkmcnt(0)
	v_add_f32_e32 v18, v18, v20
	v_fmamk_f32 v18, v18, 0x3b800000, v54
	v_mul_f32_e32 v20, 0x4b800000, v18
	v_cmp_gt_f32_e64 s[4:5], s29, v18
	v_mul_f32_e32 v25, v21, v39
	v_fma_f32 v42, -v38, v25, v21
	v_cndmask_b32_e64 v18, v18, v20, s[4:5]
	v_rsq_f32_e32 v20, v18
	v_fmac_f32_e32 v25, v42, v39
	v_fma_f32 v21, -v38, v25, v21
	v_div_fmas_f32 v18, v21, v39, v25
	v_mul_f32_e32 v21, 0x45800000, v20
	v_cndmask_b32_e64 v20, v20, v21, s[4:5]
	v_div_fixup_f32 v18, v18, v24, v66
	v_pk_mul_f32 v[24:25], v[56:57], v[20:21] op_sel_hi:[1,0]
	s_waitcnt vmcnt(0)
	v_pk_mul_f32 v[10:11], v[10:11], v[24:25]
	s_nop 0
	v_pk_mul_f32 v[10:11], v[22:23], v[10:11]
	v_pk_mul_f32 v[22:23], v[36:37], v[20:21] op_sel_hi:[1,0]
	v_cvt_pk_bf16_f32 v10, v10, v11
	v_pk_mul_f32 v[12:13], v[12:13], v[22:23]
	s_nop 0
	v_pk_mul_f32 v[12:13], v[48:49], v[12:13]
	s_nop 0
	v_cvt_pk_bf16_f32 v11, v12, v13
	v_pk_mul_f32 v[12:13], v[34:35], v[20:21] op_sel_hi:[1,0]
	s_nop 0
	v_pk_mul_f32 v[6:7], v[6:7], v[12:13]
	s_nop 0
	v_pk_mul_f32 v[6:7], v[40:41], v[6:7]
	s_nop 0
	v_cvt_pk_bf16_f32 v12, v6, v7
	v_pk_mul_f32 v[6:7], v[32:33], v[20:21] op_sel_hi:[1,0]
	v_lshlrev_b32_e32 v21, 16, v3
	v_pk_mul_f32 v[6:7], v[8:9], v[6:7]
	v_and_b32_e32 v3, 0xffff0000, v3
	v_pk_mul_f32 v[6:7], v[18:19], v[6:7]
	v_and_b32_e32 v33, 0xffff0000, v2
	v_cvt_pk_bf16_f32 v13, v6, v7
	global_store_dwordx4 v[28:29], v[10:13], off offset:-16
	global_load_dwordx4 v[6:9], v[26:27], off offset:32
	s_nop 0
	v_mul_f32_e32 v10, 0xbfb8aa3b, v21
	v_mul_f32_e32 v11, 0xbfb8aa3b, v3
	v_exp_f32_e32 v10, v10
	v_exp_f32_e32 v11, v11
	s_nop 0
	v_pk_add_f32 v[18:19], v[10:11], 1.0 op_sel_hi:[1,0]
	global_load_dwordx4 v[10:13], v[26:27], off offset:48
	v_div_scale_f32 v22, s[4:5], v19, v19, v3
	v_rcp_f32_e32 v23, v22
	s_nop 0
	v_fma_f32 v24, -v22, v23, 1.0
	v_fmac_f32_e32 v23, v24, v23
	v_div_scale_f32 v24, vcc, v3, v19, v3
	v_mul_f32_e32 v25, v24, v23
	v_fma_f32 v32, -v22, v25, v24
	v_fmac_f32_e32 v25, v32, v23
	v_fma_f32 v22, -v22, v25, v24
	v_div_scale_f32 v24, s[4:5], v18, v18, v21
	v_rcp_f32_e32 v32, v24
	v_div_fmas_f32 v22, v22, v23, v25
	v_div_fixup_f32 v19, v22, v19, v3
	v_lshlrev_b32_e32 v25, 16, v2
	v_fma_f32 v3, -v24, v32, 1.0
	v_fmac_f32_e32 v32, v3, v32
	v_mul_f32_e32 v2, 0xbfb8aa3b, v25
	v_mul_f32_e32 v3, 0xbfb8aa3b, v33
	v_exp_f32_e32 v2, v2
	v_exp_f32_e32 v3, v3
	v_div_scale_f32 v22, vcc, v21, v18, v21
	v_mul_f32_e32 v23, v22, v32
	v_fma_f32 v34, -v24, v23, v22
	v_fmac_f32_e32 v23, v34, v32
	v_pk_add_f32 v[2:3], v[2:3], 1.0 op_sel_hi:[1,0]
	v_fma_f32 v22, -v24, v23, v22
	v_div_scale_f32 v24, s[4:5], v3, v3, v33
	v_rcp_f32_e32 v34, v24
	v_div_fmas_f32 v22, v22, v32, v23
	v_div_fixup_f32 v18, v22, v18, v21
	v_fma_f32 v21, -v24, v34, 1.0
	v_fmac_f32_e32 v34, v21, v34
	v_div_scale_f32 v21, vcc, v33, v3, v33
	v_mul_f32_e32 v22, v21, v34
	v_fma_f32 v23, -v24, v22, v21
	v_fmac_f32_e32 v22, v23, v34
	v_div_scale_f32 v23, s[4:5], v2, v2, v25
	v_fma_f32 v21, -v24, v22, v21
	v_rcp_f32_e32 v24, v23
	v_div_fmas_f32 v21, v21, v34, v22
	v_div_fixup_f32 v3, v21, v3, v33
	v_fma_f32 v21, -v23, v24, 1.0
	v_fmac_f32_e32 v24, v21, v24
	v_div_scale_f32 v21, vcc, v25, v2, v25
	v_mul_f32_e32 v22, v21, v24
	v_fma_f32 v32, -v23, v22, v21
	v_fmac_f32_e32 v22, v32, v24
	v_fma_f32 v21, -v23, v22, v21
	v_div_fmas_f32 v21, v21, v24, v22
	v_pk_mul_f32 v[14:15], v[14:15], v[20:21] op_sel_hi:[1,0]
	v_div_fixup_f32 v2, v21, v2, v25
	v_lshlrev_b32_e32 v21, 16, v4
	v_and_b32_e32 v4, 0xffff0000, v4
	s_waitcnt vmcnt(1)
	v_pk_mul_f32 v[6:7], v[6:7], v[14:15]
	s_nop 0
	v_pk_mul_f32 v[2:3], v[2:3], v[6:7]
	v_pk_mul_f32 v[14:15], v[60:61], v[20:21] op_sel_hi:[1,0]
	v_cvt_pk_bf16_f32 v2, v2, v3
	v_mul_f32_e32 v3, 0xbfb8aa3b, v21
	v_exp_f32_e32 v6, v3
	v_mul_f32_e32 v3, 0xbfb8aa3b, v4
	v_exp_f32_e32 v7, v3
	v_pk_mul_f32 v[8:9], v[8:9], v[14:15]
	v_pk_add_f32 v[6:7], v[6:7], 1.0 op_sel_hi:[1,0]
	s_nop 0
	v_div_scale_f32 v14, s[4:5], v7, v7, v4
	v_rcp_f32_e32 v15, v14
	v_pk_mul_f32 v[8:9], v[18:19], v[8:9]
	s_nop 0
	v_cvt_pk_bf16_f32 v3, v8, v9
	v_pk_mul_f32 v[8:9], v[16:17], v[20:21] op_sel_hi:[1,0]
	s_waitcnt vmcnt(0)
	v_pk_mul_f32 v[8:9], v[10:11], v[8:9]
	v_fma_f32 v10, -v14, v15, 1.0
	v_fmac_f32_e32 v15, v10, v15
	v_div_scale_f32 v10, vcc, v4, v7, v4
	v_mul_f32_e32 v11, v10, v15
	v_fma_f32 v16, -v14, v11, v10
	v_fmac_f32_e32 v11, v16, v15
	v_fma_f32 v10, -v14, v11, v10
	v_div_scale_f32 v14, s[4:5], v6, v6, v21
	v_rcp_f32_e32 v16, v14
	v_div_fmas_f32 v10, v10, v15, v11
	v_div_fixup_f32 v7, v10, v7, v4
	v_and_b32_e32 v15, 0xffff0000, v5
	v_fma_f32 v4, -v14, v16, 1.0
	v_fmac_f32_e32 v16, v4, v16
	v_div_scale_f32 v4, vcc, v21, v6, v21
	v_mul_f32_e32 v10, v4, v16
	v_fma_f32 v11, -v14, v10, v4
	v_fmac_f32_e32 v10, v11, v16
	v_fma_f32 v11, -v14, v10, v4
	v_lshlrev_b32_e32 v14, 16, v5
	v_mul_f32_e32 v4, 0xbfb8aa3b, v14
	v_mul_f32_e32 v5, 0xbfb8aa3b, v15
	v_exp_f32_e32 v4, v4
	v_exp_f32_e32 v5, v5
	v_div_fmas_f32 v10, v11, v16, v10
	v_div_fixup_f32 v6, v10, v6, v21
	v_pk_mul_f32 v[6:7], v[6:7], v[8:9]
	v_pk_add_f32 v[8:9], v[4:5], 1.0 op_sel_hi:[1,0]
	v_cvt_pk_bf16_f32 v4, v6, v7
	v_div_scale_f32 v5, s[4:5], v9, v9, v15
	v_rcp_f32_e32 v10, v5
	v_pk_mul_f32 v[6:7], v[30:31], v[20:21] op_sel_hi:[1,0]
	v_fma_f32 v11, -v5, v10, 1.0
	v_fmac_f32_e32 v10, v11, v10
	v_div_scale_f32 v11, vcc, v15, v9, v15
	v_pk_mul_f32 v[6:7], v[12:13], v[6:7] op_sel:[0,1] op_sel_hi:[1,0]
	v_mul_f32_e32 v12, v11, v10
	v_fma_f32 v13, -v5, v12, v11
	v_fmac_f32_e32 v12, v13, v10
	v_fma_f32 v5, -v5, v12, v11
	v_div_scale_f32 v11, s[4:5], v8, v8, v14
	v_rcp_f32_e32 v13, v11
	v_div_fmas_f32 v5, v5, v10, v12
	v_div_fixup_f32 v9, v5, v9, v15
	v_fma_f32 v5, -v11, v13, 1.0
	v_fmac_f32_e32 v13, v5, v13
	v_div_scale_f32 v5, vcc, v14, v8, v14
	v_mul_f32_e32 v10, v5, v13
	v_fma_f32 v12, -v11, v10, v5
	v_fmac_f32_e32 v10, v12, v13
	v_fma_f32 v5, -v11, v10, v5
	v_div_fmas_f32 v5, v5, v13, v10
	v_div_fixup_f32 v8, v5, v8, v14
	v_pk_mul_f32 v[6:7], v[8:9], v[6:7]
	v_cmp_lt_i32_e32 vcc, s30, v1
	v_cvt_pk_bf16_f32 v5, v6, v7
	global_store_dwordx4 v[28:29], v[2:5], off
	s_or_b64 s[22:23], vcc, s[22:23]
	v_lshl_add_u64 v[28:29], v[28:29], 0, s[16:17]
	s_andn2_b64 exec, exec, s[22:23]
	s_cbranch_execnz .LBB0_742

; DI float lo_bf(unsigned u) { return __uint_as_float(u << 16); }
; DI float hi_bf(unsigned u) { return __uint_as_float(u & 0xffff0000u); }
; DI void phase_mix_gla(const Params& p, int j, int row_lo, int nrows, int bid, int nb) {
;     ...
;             const u32x4 gq0 = *(const u32x4*)(row + 6144 + c0), gq1 = *(const u32x4*)(row + 6144 + c0 + 8);
; #pragma unroll
;             for (int q = 0; q < 2; ++q) { const u32x4 a = *(const u32x4*)(row + c0 + 8 * q), b = *(const u32x4*)(row + 2048 + c0 + 8 * q);
;                 o[8 * q + 0] = lo_bf(a.x) + lo_bf(b.x); o[8 * q + 1] = hi_bf(a.x) + hi_bf(b.x); o[8 * q + 2] = lo_bf(a.y) + lo_bf(b.y); o[8 * q + 3] = hi_bf(a.y) + hi_bf(b.y);
;                 o[8 * q + 4] = lo_bf(a.z) + lo_bf(b.z); o[8 * q + 5] = hi_bf(a.z) + hi_bf(b.z); o[8 * q + 6] = lo_bf(a.w) + lo_bf(b.w); o[8 * q + 7] = hi_bf(a.w) + hi_bf(b.w); }
;             float ss = 0.f;
; #pragma unroll
;             for (int i = 0; i < 16; ++i) ss += o[i] * o[i];
; #pragma unroll
;             for (int m = 8; m > 0; m >>= 1) ss += __shfl_xor(ss, m);
;             const float rs = rsqrtf(ss * (1.f / 256.f) + LN_EPS);
.LBB0_746:
	v_lshl_add_u64 v[2:3], v[28:29], 0, s[20:21]
	global_load_dwordx4 v[22:25], v[28:29], off offset:-16
	global_load_dwordx4 v[14:17], v[2:3], off offset:16
	v_lshl_add_u64 v[2:3], v[28:29], 0, s[22:23]
	global_load_dwordx4 v[18:21], v[2:3], off offset:16
	v_add_co_u32_e32 v2, vcc, 0xffffd000, v28
	v_add_u32_e32 v55, 0x80, v55
	s_nop 0
	v_addc_co_u32_e32 v3, vcc, -1, v29, vcc
	global_load_dwordx4 v[58:61], v[2:3], off offset:-16
	v_add_co_u32_e32 v30, vcc, 0xffffe000, v28
	s_waitcnt vmcnt(3)
	v_lshlrev_b32_e32 v57, 16, v24
	v_addc_co_u32_e32 v31, vcc, -1, v29, vcc
	global_load_dwordx4 v[62:65], v[30:31], off offset:-16
	global_load_dwordx4 v[2:5], v[28:29], off
	global_load_dwordx4 v[6:9], v[26:27], off offset:16
	global_load_dwordx4 v[10:13], v[26:27], off
	v_and_b32_e32 v24, 0xffff0000, v24
	s_waitcnt vmcnt(6)
	v_and_b32_e32 v30, 0xffff0000, v17
	v_lshlrev_b32_e32 v31, 16, v17
	s_waitcnt vmcnt(5)
	v_and_b32_e32 v32, 0xffff0000, v21
	v_lshlrev_b32_e32 v33, 16, v21
	v_mul_f32_e32 v17, 0xbfb8aa3b, v57
	v_mul_f32_e32 v21, 0xbfb8aa3b, v24
	v_lshlrev_b32_e32 v66, 16, v23
	v_and_b32_e32 v23, 0xffff0000, v23
	v_exp_f32_e32 v40, v17
	v_exp_f32_e32 v41, v21
	v_mul_f32_e32 v38, 0xbfb8aa3b, v66
	v_mul_f32_e32 v39, 0xbfb8aa3b, v23
	v_exp_f32_e32 v48, v38
	v_exp_f32_e32 v49, v39
	v_pk_add_f32 v[40:41], v[40:41], 1.0 op_sel_hi:[1,0]
	s_waitcnt vmcnt(4)
	v_lshlrev_b32_e32 v36, 16, v59
	v_div_scale_f32 v17, s[4:5], v41, v41, v24
	v_and_b32_e32 v37, 0xffff0000, v59
	v_pk_add_f32 v[48:49], v[48:49], 1.0 op_sel_hi:[1,0]
	v_div_scale_f32 v59, s[4:5], v40, v40, v57
	v_pk_add_f32 v[30:31], v[30:31], v[32:33]
	v_lshlrev_b32_e32 v32, 16, v61
	v_and_b32_e32 v33, 0xffff0000, v61
	v_div_scale_f32 v61, s[6:7], v49, v49, v23
	v_rcp_f32_e32 v67, v59
	v_rcp_f32_e32 v68, v61
	v_div_scale_f32 v21, vcc, v24, v41, v24
	v_fma_f32 v71, -v59, v67, 1.0
	v_lshlrev_b32_e32 v34, 16, v60
	v_and_b32_e32 v35, 0xffff0000, v60
	v_div_scale_f32 v60, s[4:5], v57, v40, v57
	v_fma_f32 v72, -v61, v68, 1.0
	v_fmac_f32_e32 v67, v71, v67
	v_fmac_f32_e32 v68, v72, v68
	v_mul_f32_e32 v71, v60, v67
	v_fma_f32 v74, -v59, v71, v60
	v_fmac_f32_e32 v71, v74, v67
	v_pk_mul_f32 v[38:39], v[30:31], v[30:31]
	s_waitcnt vmcnt(3)
	v_lshlrev_b32_e32 v42, 16, v65
	v_and_b32_e32 v43, 0xffff0000, v65
	v_rcp_f32_e32 v65, v17
	v_lshlrev_b32_e32 v46, 16, v63
	v_and_b32_e32 v47, 0xffff0000, v63
	v_div_scale_f32 v63, s[6:7], v23, v49, v23
	v_fma_f32 v70, -v17, v65, 1.0
	v_fmac_f32_e32 v65, v70, v65
	v_mul_f32_e32 v70, v21, v65
	v_fma_f32 v73, -v17, v70, v21
	v_lshlrev_b32_e32 v44, 16, v64
	v_and_b32_e32 v45, 0xffff0000, v64
	v_div_scale_f32 v64, s[28:29], v48, v48, v66
	v_mul_f32_e32 v72, v63, v68
	v_fmac_f32_e32 v70, v73, v65
	v_rcp_f32_e32 v69, v64
	v_fma_f32 v75, -v61, v72, v63
	v_fma_f32 v17, -v17, v70, v21
	v_fmac_f32_e32 v72, v75, v68
	v_fma_f32 v21, -v59, v71, v60
	v_div_fmas_f32 v17, v17, v65, v70
	s_mov_b64 vcc, s[4:5]
	v_fma_f32 v59, -v61, v72, v63
	v_div_fixup_f32 v41, v17, v41, v24
	v_div_fmas_f32 v17, v21, v67, v71
	s_mov_b64 vcc, s[6:7]
	v_div_fixup_f32 v40, v17, v40, v57
	v_div_fmas_f32 v17, v59, v68, v72
	v_div_fixup_f32 v49, v17, v49, v23
	v_fma_f32 v17, -v64, v69, 1.0
	v_fmac_f32_e32 v69, v17, v69
	v_div_scale_f32 v17, vcc, v66, v48, v66
	v_mul_f32_e32 v21, v17, v69
	v_fma_f32 v23, -v64, v21, v17
	v_fmac_f32_e32 v21, v23, v69
	v_fma_f32 v17, -v64, v21, v17
	v_div_fmas_f32 v17, v17, v69, v21
	v_div_fixup_f32 v48, v17, v48, v66
	v_lshlrev_b32_e32 v17, 16, v22
	v_and_b32_e32 v21, 0xffff0000, v22
	v_mul_f32_e32 v22, 0xbfb8aa3b, v17
	v_mul_f32_e32 v23, 0xbfb8aa3b, v21
	v_exp_f32_e32 v22, v22
	v_exp_f32_e32 v23, v23
	v_lshlrev_b32_e32 v60, 16, v58
	v_and_b32_e32 v61, 0xffff0000, v58
	v_lshlrev_b32_e32 v58, 16, v62
	v_pk_add_f32 v[22:23], v[22:23], 1.0 op_sel_hi:[1,0]
	v_and_b32_e32 v59, 0xffff0000, v62
	v_div_scale_f32 v24, s[4:5], v23, v23, v21
	v_rcp_f32_e32 v57, v24
	v_lshlrev_b32_e32 v68, 16, v25
	v_and_b32_e32 v69, 0xffff0000, v25
	v_mul_f32_e32 v25, 0xbfb8aa3b, v69
	v_fma_f32 v62, -v24, v57, 1.0
	v_fmac_f32_e32 v57, v62, v57
	v_div_scale_f32 v62, vcc, v21, v23, v21
	v_mul_f32_e32 v63, v62, v57
	v_fma_f32 v64, -v24, v63, v62
	v_fmac_f32_e32 v63, v64, v57
	v_fma_f32 v24, -v24, v63, v62
	v_div_scale_f32 v62, s[4:5], v22, v22, v17
	v_div_fmas_f32 v24, v24, v57, v63
	v_rcp_f32_e32 v64, v62
	v_div_fixup_f32 v23, v24, v23, v21
	v_mul_f32_e32 v24, 0xbfb8aa3b, v68
	v_exp_f32_e32 v24, v24
	v_exp_f32_e32 v25, v25
	v_fma_f32 v21, -v62, v64, 1.0
	v_fmac_f32_e32 v64, v21, v64
	v_div_scale_f32 v21, vcc, v17, v22, v17
	v_pk_add_f32 v[24:25], v[24:25], 1.0 op_sel_hi:[1,0]
	v_mul_f32_e32 v57, v21, v64
	v_div_scale_f32 v70, s[4:5], v25, v25, v69
	v_pk_add_f32 v[58:59], v[60:61], v[58:59]
	v_fma_f32 v63, -v62, v57, v21
	v_rcp_f32_e32 v71, v70
	v_pk_add_f32 v[36:37], v[36:37], v[46:47]
	v_pk_mul_f32 v[60:61], v[58:59], v[58:59]
	v_fmac_f32_e32 v57, v63, v64
	v_pk_mul_f32 v[46:47], v[36:37], v[36:37]
	v_fma_f32 v21, -v62, v57, v21
	v_add_f32_e32 v60, v60, v61
	v_pk_add_f32 v[34:35], v[34:35], v[44:45]
	v_div_fmas_f32 v21, v21, v64, v57
	v_add_f32_e32 v46, v46, v60
	v_pk_mul_f32 v[44:45], v[34:35], v[34:35]
	v_div_fixup_f32 v22, v21, v22, v17
	v_fma_f32 v17, -v70, v71, 1.0
	v_add_f32_e32 v46, v47, v46
	v_pk_add_f32 v[32:33], v[32:33], v[42:43]
	v_fmac_f32_e32 v71, v17, v71
	v_lshlrev_b32_e32 v62, 16, v16
	v_and_b32_e32 v63, 0xffff0000, v16
	v_lshlrev_b32_e32 v16, 16, v20
	v_and_b32_e32 v17, 0xffff0000, v20
	v_add_f32_e32 v44, v44, v46
	v_pk_mul_f32 v[42:43], v[32:33], v[32:33]
	v_pk_add_f32 v[16:17], v[62:63], v[16:17]
	v_lshlrev_b32_e32 v62, 16, v15
	v_and_b32_e32 v63, 0xffff0000, v15
	v_lshlrev_b32_e32 v66, 16, v14
	v_and_b32_e32 v67, 0xffff0000, v14
	v_lshlrev_b32_e32 v14, 16, v18
	v_and_b32_e32 v15, 0xffff0000, v18
	v_add_f32_e32 v44, v45, v44
	v_pk_add_f32 v[14:15], v[66:67], v[14:15]
	v_add_f32_e32 v42, v42, v44
	v_lshlrev_b32_e32 v64, 16, v19
	v_and_b32_e32 v65, 0xffff0000, v19
	v_pk_mul_f32 v[18:19], v[14:15], v[14:15]
	v_add_f32_e32 v42, v43, v42
	v_pk_add_f32 v[62:63], v[62:63], v[64:65]
	v_add_f32_e32 v18, v18, v42
	v_pk_mul_f32 v[64:65], v[62:63], v[62:63]
	v_add_f32_e32 v18, v19, v18
	v_add_f32_e32 v18, v64, v18
	v_pk_mul_f32 v[20:21], v[16:17], v[16:17]
	v_add_f32_e32 v18, v65, v18
	v_add_f32_e32 v18, v20, v18
	v_add_f32_e32 v18, v21, v18
	v_add_f32_e32 v18, v39, v18
	v_add_f32_e32 v18, v38, v18
	s_nop 1
	v_mov_b32_dpp v19, v18 row_ror:8 row_mask:0xf bank_mask:0xf
	v_div_scale_f32 v57, vcc, v69, v25, v69
	v_mul_f32_e32 v72, v57, v71
	v_fma_f32 v73, -v70, v72, v57
	s_waitcnt lgkmcnt(0)
; DI unsigned pk2(float lo, float hi) { f32x2 v = {lo, hi}; bfv2 b = __builtin_convertvector(v, bfv2); return __builtin_bit_cast(unsigned, b); }
; DI float lo_bf(unsigned u) { return __uint_as_float(u << 16); }
; DI float hi_bf(unsigned u) { return __uint_as_float(u & 0xffff0000u); }
; DI float silu(float x) { return x / (1.f + __expf(-x)); }
; DI void phase_mix_gla(const Params& p, int j, int row_lo, int nrows, int bid, int nb) {
;     ...
;             for (int m = 8; m > 0; m >>= 1) ss += __shfl_xor(ss, m);
;             const float rs = rsqrtf(ss * (1.f / 256.f) + LN_EPS);
;             const int vc = (lane & 15) * 16;
; #pragma unroll
;             for (int q = 0; q < 2; ++q) { const u32x4 gq = q ? gq1 : gq0;
;                 const f32x4 w0 = *(const f32x4*)(gnw + vc + 8 * q), w1 = *(const f32x4*)(gnw + vc + 8 * q + 4);
;                 u32x4 y;
;                 y.x = pk2(o[8 * q + 0] * rs * w0[0] * silu(lo_bf(gq.x)), o[8 * q + 1] * rs * w0[1] * silu(hi_bf(gq.x)));
;                 y.y = pk2(o[8 * q + 2] * rs * w0[2] * silu(lo_bf(gq.y)), o[8 * q + 3] * rs * w0[3] * silu(hi_bf(gq.y)));
;                 y.z = pk2(o[8 * q + 4] * rs * w1[0] * silu(lo_bf(gq.z)), o[8 * q + 5] * rs * w1[1] * silu(hi_bf(gq.z)));
;                 y.w = pk2(o[8 * q + 6] * rs * w1[2] * silu(lo_bf(gq.w)), o[8 * q + 7] * rs * w1[3] * silu(hi_bf(gq.w)));
;                 *(u32x4*)(row + 6144 + c0 + 8 * q) = y; }
	v_add_f32_e32 v18, v18, v19
	s_nop 1
	v_mov_b32_dpp v21, v18 row_ror:4 row_mask:0xf bank_mask:0xf
	v_fmac_f32_e32 v72, v73, v71
	v_fma_f32 v20, -v70, v72, v57
	v_div_fmas_f32 v20, v20, v71, v72
	v_div_fixup_f32 v19, v20, v25, v69
	s_waitcnt lgkmcnt(0)
	v_add_f32_e32 v18, v18, v21
	s_nop 1
	v_mov_b32_dpp v20, v18 row_ror:2 row_mask:0xf bank_mask:0xf
	v_div_scale_f32 v38, s[4:5], v24, v24, v68
	v_rcp_f32_e32 v39, v38
	s_waitcnt lgkmcnt(0)
	v_add_f32_e32 v18, v18, v20
	s_nop 1
	v_mov_b32_dpp v20, v18 row_ror:1 row_mask:0xf bank_mask:0xf
	v_fma_f32 v21, -v38, v39, 1.0
	v_fmac_f32_e32 v39, v21, v39
	v_div_scale_f32 v21, vcc, v68, v24, v68
	s_waitcnt lgkmcnt(0)
	v_add_f32_e32 v18, v18, v20
	v_fmamk_f32 v18, v18, 0x3b800000, v56
	v_mul_f32_e32 v20, 0x4b800000, v18
	v_cmp_gt_f32_e64 s[4:5], s26, v18
	v_mul_f32_e32 v25, v21, v39
	v_fma_f32 v42, -v38, v25, v21
	v_cndmask_b32_e64 v18, v18, v20, s[4:5]
	v_rsq_f32_e32 v20, v18
	v_fmac_f32_e32 v25, v42, v39
	v_fma_f32 v21, -v38, v25, v21
	v_div_fmas_f32 v18, v21, v39, v25
	v_mul_f32_e32 v21, 0x45800000, v20
	v_cndmask_b32_e64 v20, v20, v21, s[4:5]
	v_div_fixup_f32 v18, v18, v24, v68
	v_pk_mul_f32 v[24:25], v[58:59], v[20:21] op_sel_hi:[1,0]
	s_waitcnt vmcnt(0)
	v_pk_mul_f32 v[10:11], v[10:11], v[24:25]
	s_nop 0
	v_pk_mul_f32 v[10:11], v[22:23], v[10:11]
	v_pk_mul_f32 v[22:23], v[36:37], v[20:21] op_sel_hi:[1,0]
	v_cvt_pk_bf16_f32 v10, v10, v11
	v_pk_mul_f32 v[12:13], v[12:13], v[22:23]
	s_nop 0
	v_pk_mul_f32 v[12:13], v[48:49], v[12:13]
	s_nop 0
	v_cvt_pk_bf16_f32 v11, v12, v13
	v_pk_mul_f32 v[12:13], v[34:35], v[20:21] op_sel_hi:[1,0]
	s_nop 0
	v_pk_mul_f32 v[6:7], v[6:7], v[12:13]
	s_nop 0
	v_pk_mul_f32 v[6:7], v[40:41], v[6:7]
	s_nop 0
	v_cvt_pk_bf16_f32 v12, v6, v7
	v_pk_mul_f32 v[6:7], v[32:33], v[20:21] op_sel_hi:[1,0]
	v_lshlrev_b32_e32 v21, 16, v3
	v_pk_mul_f32 v[6:7], v[8:9], v[6:7]
	v_and_b32_e32 v3, 0xffff0000, v3
	v_pk_mul_f32 v[6:7], v[18:19], v[6:7]
	v_and_b32_e32 v33, 0xffff0000, v2
	v_cvt_pk_bf16_f32 v13, v6, v7
	global_store_dwordx4 v[28:29], v[10:13], off offset:-16
	global_load_dwordx4 v[6:9], v[26:27], off offset:32
	s_nop 0
	v_mul_f32_e32 v10, 0xbfb8aa3b, v21
	v_mul_f32_e32 v11, 0xbfb8aa3b, v3
	v_exp_f32_e32 v10, v10
	v_exp_f32_e32 v11, v11
	s_nop 0
	v_pk_add_f32 v[18:19], v[10:11], 1.0 op_sel_hi:[1,0]
	global_load_dwordx4 v[10:13], v[26:27], off offset:48
	v_div_scale_f32 v22, s[4:5], v19, v19, v3
	v_rcp_f32_e32 v23, v22
	s_nop 0
	v_fma_f32 v24, -v22, v23, 1.0
	v_fmac_f32_e32 v23, v24, v23
	v_div_scale_f32 v24, vcc, v3, v19, v3
	v_mul_f32_e32 v25, v24, v23
	v_fma_f32 v32, -v22, v25, v24
	v_fmac_f32_e32 v25, v32, v23
	v_fma_f32 v22, -v22, v25, v24
	v_div_scale_f32 v24, s[4:5], v18, v18, v21
	v_rcp_f32_e32 v32, v24
	v_div_fmas_f32 v22, v22, v23, v25
	v_div_fixup_f32 v19, v22, v19, v3
	v_lshlrev_b32_e32 v25, 16, v2
	v_fma_f32 v3, -v24, v32, 1.0
	v_fmac_f32_e32 v32, v3, v32
	v_mul_f32_e32 v2, 0xbfb8aa3b, v25
	v_mul_f32_e32 v3, 0xbfb8aa3b, v33
	v_exp_f32_e32 v2, v2
	v_exp_f32_e32 v3, v3
	v_div_scale_f32 v22, vcc, v21, v18, v21
	v_mul_f32_e32 v23, v22, v32
	v_fma_f32 v34, -v24, v23, v22
	v_fmac_f32_e32 v23, v34, v32
	v_pk_add_f32 v[2:3], v[2:3], 1.0 op_sel_hi:[1,0]
	v_fma_f32 v22, -v24, v23, v22
	v_div_scale_f32 v24, s[4:5], v3, v3, v33
	v_rcp_f32_e32 v34, v24
	v_div_fmas_f32 v22, v22, v32, v23
	v_div_fixup_f32 v18, v22, v18, v21
	v_fma_f32 v21, -v24, v34, 1.0
	v_fmac_f32_e32 v34, v21, v34
	v_div_scale_f32 v21, vcc, v33, v3, v33
	v_mul_f32_e32 v22, v21, v34
	v_fma_f32 v23, -v24, v22, v21
	v_fmac_f32_e32 v22, v23, v34
	v_div_scale_f32 v23, s[4:5], v2, v2, v25
	v_fma_f32 v21, -v24, v22, v21
	v_rcp_f32_e32 v24, v23
	v_div_fmas_f32 v21, v21, v34, v22
	v_div_fixup_f32 v3, v21, v3, v33
	v_fma_f32 v21, -v23, v24, 1.0
	v_fmac_f32_e32 v24, v21, v24
	v_div_scale_f32 v21, vcc, v25, v2, v25
	v_mul_f32_e32 v22, v21, v24
	v_fma_f32 v32, -v23, v22, v21
	v_fmac_f32_e32 v22, v32, v24
	v_fma_f32 v21, -v23, v22, v21
	v_div_fmas_f32 v21, v21, v24, v22
	v_pk_mul_f32 v[14:15], v[14:15], v[20:21] op_sel_hi:[1,0]
	v_div_fixup_f32 v2, v21, v2, v25
	v_lshlrev_b32_e32 v21, 16, v4
	v_and_b32_e32 v4, 0xffff0000, v4
	s_waitcnt vmcnt(1)
	v_pk_mul_f32 v[6:7], v[6:7], v[14:15]
	s_nop 0
	v_pk_mul_f32 v[2:3], v[2:3], v[6:7]
	v_pk_mul_f32 v[14:15], v[62:63], v[20:21] op_sel_hi:[1,0]
	v_cvt_pk_bf16_f32 v2, v2, v3
	v_mul_f32_e32 v3, 0xbfb8aa3b, v21
	v_exp_f32_e32 v6, v3
	v_mul_f32_e32 v3, 0xbfb8aa3b, v4
	v_exp_f32_e32 v7, v3
	v_pk_mul_f32 v[8:9], v[8:9], v[14:15]
	v_pk_add_f32 v[6:7], v[6:7], 1.0 op_sel_hi:[1,0]
	s_nop 0
	v_div_scale_f32 v14, s[4:5], v7, v7, v4
	v_rcp_f32_e32 v15, v14
	v_pk_mul_f32 v[8:9], v[18:19], v[8:9]
	s_nop 0
	v_cvt_pk_bf16_f32 v3, v8, v9
	v_pk_mul_f32 v[8:9], v[16:17], v[20:21] op_sel_hi:[1,0]
	s_waitcnt vmcnt(0)
	v_pk_mul_f32 v[8:9], v[10:11], v[8:9]
	v_fma_f32 v10, -v14, v15, 1.0
	v_fmac_f32_e32 v15, v10, v15
	v_div_scale_f32 v10, vcc, v4, v7, v4
	v_mul_f32_e32 v11, v10, v15
	v_fma_f32 v16, -v14, v11, v10
	v_fmac_f32_e32 v11, v16, v15
	v_fma_f32 v10, -v14, v11, v10
	v_div_scale_f32 v14, s[4:5], v6, v6, v21
	v_rcp_f32_e32 v16, v14
	v_div_fmas_f32 v10, v10, v15, v11
	v_div_fixup_f32 v7, v10, v7, v4
	v_and_b32_e32 v15, 0xffff0000, v5
	v_fma_f32 v4, -v14, v16, 1.0
	v_fmac_f32_e32 v16, v4, v16
	v_div_scale_f32 v4, vcc, v21, v6, v21
	v_mul_f32_e32 v10, v4, v16
	v_fma_f32 v11, -v14, v10, v4
	v_fmac_f32_e32 v10, v11, v16
	v_fma_f32 v11, -v14, v10, v4
	v_lshlrev_b32_e32 v14, 16, v5
	v_mul_f32_e32 v4, 0xbfb8aa3b, v14
	v_mul_f32_e32 v5, 0xbfb8aa3b, v15
	v_exp_f32_e32 v4, v4
	v_exp_f32_e32 v5, v5
	v_div_fmas_f32 v10, v11, v16, v10
	v_div_fixup_f32 v6, v10, v6, v21
	v_pk_mul_f32 v[6:7], v[6:7], v[8:9]
	v_pk_add_f32 v[8:9], v[4:5], 1.0 op_sel_hi:[1,0]
	v_cvt_pk_bf16_f32 v4, v6, v7
	v_div_scale_f32 v5, s[4:5], v9, v9, v15
	v_rcp_f32_e32 v10, v5
	v_pk_mul_f32 v[6:7], v[30:31], v[20:21] op_sel_hi:[1,0]
	v_fma_f32 v11, -v5, v10, 1.0
	v_fmac_f32_e32 v10, v11, v10
	v_div_scale_f32 v11, vcc, v15, v9, v15
	v_pk_mul_f32 v[6:7], v[12:13], v[6:7] op_sel:[0,1] op_sel_hi:[1,0]
	v_mul_f32_e32 v12, v11, v10
	v_fma_f32 v13, -v5, v12, v11
	v_fmac_f32_e32 v12, v13, v10
	v_fma_f32 v5, -v5, v12, v11
	v_div_scale_f32 v11, s[4:5], v8, v8, v14
	v_rcp_f32_e32 v13, v11
	v_div_fmas_f32 v5, v5, v10, v12
	v_div_fixup_f32 v9, v5, v9, v15
	v_fma_f32 v5, -v11, v13, 1.0
	v_fmac_f32_e32 v13, v5, v13
	v_div_scale_f32 v5, vcc, v14, v8, v14
	v_mul_f32_e32 v10, v5, v13
	v_fma_f32 v12, -v11, v10, v5
	v_fmac_f32_e32 v10, v12, v13
	v_fma_f32 v5, -v11, v10, v5
	v_div_fmas_f32 v5, v5, v13, v10
	v_div_fixup_f32 v8, v5, v8, v14
	v_pk_mul_f32 v[6:7], v[8:9], v[6:7]
	v_cmp_lt_i32_e32 vcc, s27, v55
	v_cvt_pk_bf16_f32 v5, v6, v7
	global_store_dwordx4 v[28:29], v[2:5], off
	s_or_b64 s[18:19], vcc, s[18:19]
	v_lshl_add_u64 v[28:29], v[28:29], 0, s[24:25]
	s_andn2_b64 exec, exec, s[18:19]
	s_cbranch_execnz .LBB0_746
; DI unsigned xb_add(unsigned* p, unsigned v) { return __hip_atomic_fetch_add(p, v, __ATOMIC_RELAXED, __HIP_MEMORY_SCOPE_AGENT); }
; DI void mini_barrier(unsigned* cnt, unsigned expected) {
;     asm volatile("s_waitcnt vmcnt(0)" ::: "memory");
;     __syncthreads();
;     if (threadIdx.x == 0) {
;         __builtin_amdgcn_fence(__ATOMIC_RELEASE, "agent");
;         asm volatile("s_waitcnt vmcnt(0)" ::: "memory");
;         (void)xb_add(cnt, 1u);
	s_or_b64 exec, exec, s[18:19]
	s_waitcnt vmcnt(0)
	s_barrier
	s_and_saveexec_b64 s[4:5], s[40:41]
	s_cbranch_execz .LBB0_759
	s_mov_b64 s[18:19], exec
	buffer_wbl2 sc1
	s_waitcnt vmcnt(0)
	s_waitcnt vmcnt(0)
	v_mbcnt_lo_u32_b32 v2, s18, 0
	s_add_u32 s6, s10, 0x3b603900
	v_mbcnt_hi_u32_b32 v2, s19, v2
	s_addc_u32 s7, s11, 0
	v_cmp_eq_u32_e32 vcc, 0, v2
	s_and_saveexec_b64 s[20:21], vcc
	s_cbranch_execz .LBB0_750
	s_bcnt1_i32_b64 s18, s[18:19]
	v_mov_b32_e32 v2, 0
	v_mov_b32_e32 v3, s18
	global_atomic_add v2, v3, s[6:7]

; DI void phase_norm(const Params& p, int mode, int l, int row_lo, int nrows, int bid, int nb) {
;     ...
;         { const int rn = r + nw < nrows ? r + nw : r;
;           const float* srcn = mode == 0 ? xin_row(p, rn) : (const float*)vrow(p, rn);
; #pragma unroll
;           for (int i = 0; i < 8; ++i) vn[i] = *(const f32x4*)(srcn + i * 256 + lane * 4); }
;         if (mode != 0) {
;             float s = 0.f;
; #pragma unroll
;             for (int i = 0; i < 8; ++i) s += v[i][0] + v[i][1] + v[i][2] + v[i][3];
;             s = wave_sum(s); const float mu = s * (1.f / 2048.f);
;             float q = 0.f;
; #pragma unroll
;             for (int i = 0; i < 8; ++i) { const f32x4 d = v[i] - mu; q += d[0] * d[0] + d[1] * d[1] + d[2] * d[2] + d[3] * d[3]; }
;             q = wave_sum(q); const float rs = rsqrtf(q * (1.f / 2048.f) + LN_EPS);
;             if (mode == 1 && lane == 0) { stats[2 * r] = mu; stats[2 * r + 1] = rs; }
.LBB0_936:
	v_mov_b64_e32 v[56:57], v[4:5]
	v_mov_b64_e32 v[54:55], v[2:3]
	v_add_u32_e32 v2, s29, v66
	v_add_u32_e32 v2, 0xffffff00, v2
	v_mov_b64_e32 v[64:65], v[16:17]
	v_mov_b64_e32 v[60:61], v[8:9]
	v_cmp_gt_i32_e64 s[4:5], s28, v2
	v_mov_b64_e32 v[62:63], v[14:15]
	v_mov_b64_e32 v[58:59], v[6:7]
	v_cndmask_b32_e64 v6, v66, v2, s[4:5]
	v_add_f32_e32 v2, v50, v51
	v_add_f32_e32 v2, v52, v2
	v_add_f32_e32 v3, v62, v63
	v_add_f32_e32 v2, v53, v2
	v_add_f32_e32 v3, v64, v3
	v_add_f32_e32 v2, 0, v2
	v_add_f32_e32 v3, v65, v3
	v_add_f32_e32 v2, v3, v2
	v_add_f32_e32 v3, v58, v59
	v_add_f32_e32 v3, v60, v3
	v_add_f32_e32 v3, v61, v3
	v_add_f32_e32 v2, v3, v2
	v_add_f32_e32 v3, v54, v55
	v_mov_b64_e32 v[48:49], v[28:29]
	v_mov_b64_e32 v[40:41], v[24:25]
	v_add_f32_e32 v3, v56, v3
	v_mov_b64_e32 v[46:47], v[26:27]
	v_mov_b64_e32 v[38:39], v[22:23]
	v_add_f32_e32 v3, v57, v3
	v_add_f32_e32 v9, v3, v2
	v_mov_b32_e32 v2, v38
	v_mov_b32_e32 v3, v46
	v_mov_b32_e32 v4, v39
	v_mov_b32_e32 v5, v47
	v_pk_add_f32 v[2:3], v[2:3], v[4:5]
	v_mov_b32_e32 v4, v40
	v_mov_b32_e32 v5, v48
	v_pk_add_f32 v[2:3], v[4:5], v[2:3]
	v_mov_b32_e32 v4, v41
	v_mov_b32_e32 v5, v49
	v_mov_b64_e32 v[36:37], v[20:21]
	v_mov_b64_e32 v[32:33], v[12:13]
	v_pk_add_f32 v[2:3], v[4:5], v[2:3]
	v_mov_b64_e32 v[34:35], v[18:19]
	v_mov_b64_e32 v[30:31], v[10:11]
	v_add_f32_e32 v3, v3, v9
	v_add_f32_e32 v9, v2, v3
	v_mov_b32_e32 v2, v30
	v_mov_b32_e32 v3, v34
	v_mov_b32_e32 v4, v31
	v_mov_b32_e32 v5, v35
	v_pk_add_f32 v[2:3], v[2:3], v[4:5]
	v_mov_b32_e32 v4, v32
	v_mov_b32_e32 v5, v36
	v_pk_add_f32 v[2:3], v[4:5], v[2:3]
	v_mov_b32_e32 v4, v33
	v_mov_b32_e32 v5, v37
	v_pk_add_f32 v[2:3], v[4:5], v[2:3]
	v_ashrrev_i32_e32 v8, 31, v6
	v_add_f32_e32 v3, v3, v9
	v_add_f32_e32 v4, v2, v3
	v_mov_b32_e32 v5, v4
	s_nop 1
	v_permlane32_swap_b32_e32 v5, v4
	v_cmp_gt_i32_e64 s[4:5], s28, v6
	v_add_u32_e32 v7, 0xffff8000, v6
	v_lshlrev_b32_e32 v70, 2, v68
	v_cndmask_b32_e64 v3, 0, v8, s[4:5]
	s_waitcnt lgkmcnt(0)
	v_add_f32_e32 v8, v4, v5
	v_mov_b32_e32 v9, v8
	s_nop 1
	v_permlane16_swap_b32_e32 v9, v8
	v_cndmask_b32_e64 v2, v7, v6, s[4:5]
	v_mov_b32_e32 v6, s33
	v_mov_b32_e32 v7, s9
	v_cndmask_b32_e64 v5, v6, v7, s[4:5]
	v_mov_b32_e32 v4, s31
	v_mov_b32_e32 v6, s8
	v_cndmask_b32_e64 v4, v4, v6, s[4:5]
	s_waitcnt lgkmcnt(0)
	v_add_f32_e32 v6, v8, v9
	s_nop 1
	v_mov_b32_dpp v7, v6 row_ror:8 row_mask:0xf bank_mask:0xf
	v_lshlrev_b64 v[2:3], 13, v[2:3]
	v_lshl_add_u64 v[2:3], v[4:5], 0, v[2:3]
	v_lshl_add_u64 v[10:11], v[2:3], 0, v[70:71]
	v_add_co_u32_e64 v110, s[4:5], s30, v10
	s_waitcnt lgkmcnt(0)
	v_add_f32_e32 v12, v6, v7
	s_nop 1
	v_mov_b32_dpp v13, v12 row_ror:4 row_mask:0xf bank_mask:0xf
	v_addc_co_u32_e64 v111, s[4:5], 0, v11, s[4:5]
	global_load_dwordx4 v[42:45], v[10:11], off
	global_load_dwordx4 v[14:17], v[10:11], off offset:1024
	global_load_dwordx4 v[6:9], v[10:11], off offset:2048
	global_load_dwordx4 v[2:5], v[10:11], off offset:3072
	s_waitcnt lgkmcnt(0)
	v_add_f32_e32 v12, v12, v13
	s_nop 1
	v_mov_b32_dpp v13, v12 row_ror:2 row_mask:0xf bank_mask:0xf
	s_waitcnt lgkmcnt(0)
	v_add_f32_e32 v93, v12, v13
	global_load_dwordx4 v[26:29], v[110:111], off
	global_load_dwordx4 v[22:25], v[110:111], off offset:1024
	global_load_dwordx4 v[18:21], v[110:111], off offset:2048
	global_load_dwordx4 v[10:13], v[110:111], off offset:3072
	s_nop 1
	v_mov_b32_dpp v97, v93 row_ror:1 row_mask:0xf bank_mask:0xf
	s_waitcnt lgkmcnt(0)
	v_add_f32_e32 v93, v93, v97
	v_fmamk_f32 v51, v93, 0xba000000, v51
	v_fmamk_f32 v63, v93, 0xba000000, v63
	v_fmamk_f32 v115, v93, 0xba000000, v53
	v_fmamk_f32 v114, v93, 0xba000000, v52
	v_fmac_f32_e32 v50, 0xba000000, v93
	v_mul_f32_e32 v52, v51, v51
	v_fmac_f32_e32 v62, 0xba000000, v93
	v_mul_f32_e32 v53, v63, v63
	v_fmac_f32_e32 v52, v50, v50
	v_fmamk_f32 v112, v93, 0xba000000, v64
	v_fmac_f32_e32 v53, v62, v62
	v_fmac_f32_e32 v52, v114, v114
	v_fmamk_f32 v113, v93, 0xba000000, v65
	v_fmac_f32_e32 v53, v112, v112
	v_fmac_f32_e32 v52, v115, v115
	v_fmac_f32_e32 v53, v113, v113
	v_fmamk_f32 v59, v93, 0xba000000, v59
	v_add_f32_e32 v52, v52, v53
	v_fmac_f32_e32 v58, 0xba000000, v93
	v_mul_f32_e32 v53, v59, v59
	v_fmamk_f32 v110, v93, 0xba000000, v60
	v_fmac_f32_e32 v53, v58, v58
	v_fmamk_f32 v111, v93, 0xba000000, v61
	v_fmac_f32_e32 v53, v110, v110
	v_fmac_f32_e32 v53, v111, v111
	v_fmamk_f32 v55, v93, 0xba000000, v55
	v_add_f32_e32 v52, v53, v52
	v_fmac_f32_e32 v54, 0xba000000, v93
	v_mul_f32_e32 v53, v55, v55
	v_fmamk_f32 v64, v93, 0xba000000, v56
	v_fmac_f32_e32 v53, v54, v54
	v_fmamk_f32 v65, v93, 0xba000000, v57
	v_fmac_f32_e32 v53, v64, v64
	v_fmac_f32_e32 v53, v65, v65
	v_fmamk_f32 v61, v93, 0xba000000, v47
	v_fmac_f32_e32 v46, 0xba000000, v93
	v_fmamk_f32 v60, v93, 0xba000000, v39
	v_add_f32_e32 v97, v53, v52
	v_fmamk_f32 v56, v93, 0xba000000, v41
	v_fmamk_f32 v52, v93, 0xba000000, v40
	v_fmac_f32_e32 v38, 0xba000000, v93
	v_mov_b32_e32 v39, v46
	v_pk_mul_f32 v[40:41], v[60:61], v[60:61]
	v_fmamk_f32 v53, v93, 0xba000000, v48
	v_pk_fma_f32 v[40:41], v[38:39], v[38:39], v[40:41]
	v_fmamk_f32 v57, v93, 0xba000000, v49
	v_pk_fma_f32 v[40:41], v[52:53], v[52:53], v[40:41]
	v_fmamk_f32 v49, v93, 0xba000000, v35
	v_pk_fma_f32 v[40:41], v[56:57], v[56:57], v[40:41]
	v_fmac_f32_e32 v34, 0xba000000, v93
	v_add_f32_e32 v39, v41, v97
	v_fmamk_f32 v48, v93, 0xba000000, v31
	v_add_f32_e32 v39, v40, v39
	v_fmamk_f32 v41, v93, 0xba000000, v37
	v_fmamk_f32 v37, v93, 0xba000000, v36
	v_fmamk_f32 v40, v93, 0xba000000, v33
	v_fmamk_f32 v36, v93, 0xba000000, v32
	v_fmac_f32_e32 v30, 0xba000000, v93
	v_mov_b32_e32 v31, v34
	v_pk_mul_f32 v[32:33], v[48:49], v[48:49]
	s_nop 0
	v_pk_fma_f32 v[32:33], v[30:31], v[30:31], v[32:33]
	s_nop 0
	v_pk_fma_f32 v[32:33], v[36:37], v[36:37], v[32:33]
	s_nop 0
	v_pk_fma_f32 v[32:33], v[40:41], v[40:41], v[32:33]
	s_nop 0
	v_add_f32_e32 v31, v33, v39
	v_add_f32_e32 v31, v32, v31
	v_mov_b32_e32 v32, v31
	s_nop 1
	v_permlane32_swap_b32_e32 v32, v31
	s_waitcnt lgkmcnt(0)
	v_add_f32_e32 v31, v31, v32
	v_mov_b32_e32 v32, v31
	s_nop 1
	v_permlane16_swap_b32_e32 v32, v31
	s_waitcnt lgkmcnt(0)
	v_add_f32_e32 v31, v31, v32
	s_nop 1
	v_mov_b32_dpp v32, v31 row_ror:8 row_mask:0xf bank_mask:0xf
	s_waitcnt lgkmcnt(0)
	v_add_f32_e32 v31, v31, v32
	s_nop 1
	v_mov_b32_dpp v32, v31 row_ror:4 row_mask:0xf bank_mask:0xf
	s_waitcnt lgkmcnt(0)
	v_add_f32_e32 v31, v31, v32
	s_nop 1
	v_mov_b32_dpp v32, v31 row_ror:2 row_mask:0xf bank_mask:0xf
	s_waitcnt lgkmcnt(0)
	v_add_f32_e32 v31, v31, v32
	s_nop 1
	v_mov_b32_dpp v32, v31 row_ror:1 row_mask:0xf bank_mask:0xf
	s_waitcnt lgkmcnt(0)
	v_add_f32_e32 v31, v31, v32
	v_fmamk_f32 v31, v31, 0x3a000000, v67
	v_mul_f32_e32 v32, 0x4b800000, v31
	v_cmp_gt_f32_e64 s[4:5], s19, v31
	s_nop 1
	v_cndmask_b32_e64 v31, v31, v32, s[4:5]
	v_rsq_f32_e32 v31, v31
	s_nop 0
	v_mul_f32_e32 v32, 0x45800000, v31
	v_cndmask_b32_e64 v32, v31, v32, s[4:5]
	s_and_saveexec_b64 s[4:5], vcc
	s_cbranch_execz .LBB0_935
; DI void phase_norm(const Params& p, int mode, int l, int row_lo, int nrows, int bid, int nb) {
;     ...
;             if (mode == 1 && lane == 0) { stats[2 * r] = mu; stats[2 * r + 1] = rs; }
	v_mul_f32_e32 v122, 0x3a000000, v93
	v_ashrrev_i32_e32 v93, 31, v92
	v_lshl_add_u64 v[124:125], v[92:93], 2, s[20:21]
	v_mov_b32_e32 v123, v32
	global_store_dwordx2 v[124:125], v[122:123], off
	s_branch .LBB0_935

; DI void phase_norm(const Params& p, int mode, int l, int row_lo, int nrows, int bid, int nb) {
;     ...
;         { const int rn = r + nw < nrows ? r + nw : r;
;           const float* srcn = mode == 0 ? xin_row(p, rn) : (const float*)vrow(p, rn);
; #pragma unroll
;           for (int i = 0; i < 8; ++i) vn[i] = *(const f32x4*)(srcn + i * 256 + lane * 4); }
;         if (mode != 0) {
;             float s = 0.f;
; #pragma unroll
;             for (int i = 0; i < 8; ++i) s += v[i][0] + v[i][1] + v[i][2] + v[i][3];
;             s = wave_sum(s); const float mu = s * (1.f / 2048.f);
;             float q = 0.f;
; #pragma unroll
;             for (int i = 0; i < 8; ++i) { const f32x4 d = v[i] - mu; q += d[0] * d[0] + d[1] * d[1] + d[2] * d[2] + d[3] * d[3]; }
;             q = wave_sum(q); const float rs = rsqrtf(q * (1.f / 2048.f) + LN_EPS);
;             if (mode == 1 && lane == 0) { stats[2 * r] = mu; stats[2 * r + 1] = rs; }
.LBB0_942:
	v_mov_b64_e32 v[56:57], v[4:5]
	v_mov_b64_e32 v[54:55], v[2:3]
	v_mov_b32_e32 v2, v117
	v_add_u32_e32 v117, 0x100, v2
	v_mov_b64_e32 v[64:65], v[16:17]
	v_mov_b64_e32 v[60:61], v[8:9]
	v_add_u32_e32 v2, 0x200, v2
	v_cmp_gt_i32_e64 s[4:5], s27, v117
	v_mov_b64_e32 v[62:63], v[14:15]
	v_mov_b64_e32 v[58:59], v[6:7]
	v_cndmask_b32_e64 v6, v117, v2, s[4:5]
	v_add_f32_e32 v2, v50, v51
	v_add_f32_e32 v2, v52, v2
	v_add_f32_e32 v3, v62, v63
	v_add_f32_e32 v2, v53, v2
	v_add_f32_e32 v3, v64, v3
	v_add_f32_e32 v2, 0, v2
	v_add_f32_e32 v3, v65, v3
	v_add_f32_e32 v2, v3, v2
	v_add_f32_e32 v3, v58, v59
	v_add_f32_e32 v3, v60, v3
	v_add_f32_e32 v3, v61, v3
	v_add_f32_e32 v2, v3, v2
	v_add_f32_e32 v3, v54, v55
	v_mov_b64_e32 v[48:49], v[28:29]
	v_mov_b64_e32 v[40:41], v[24:25]
	v_add_f32_e32 v3, v56, v3
	v_mov_b64_e32 v[46:47], v[26:27]
	v_mov_b64_e32 v[38:39], v[22:23]
	v_add_f32_e32 v3, v57, v3
	v_add_f32_e32 v9, v3, v2
	v_mov_b32_e32 v2, v38
	v_mov_b32_e32 v3, v46
	v_mov_b32_e32 v4, v39
	v_mov_b32_e32 v5, v47
	v_pk_add_f32 v[2:3], v[2:3], v[4:5]
	v_mov_b32_e32 v4, v40
	v_mov_b32_e32 v5, v48
	v_pk_add_f32 v[2:3], v[4:5], v[2:3]
	v_mov_b32_e32 v4, v41
	v_mov_b32_e32 v5, v49
	v_mov_b64_e32 v[36:37], v[20:21]
	v_mov_b64_e32 v[32:33], v[12:13]
	v_pk_add_f32 v[2:3], v[4:5], v[2:3]
	v_mov_b64_e32 v[34:35], v[18:19]
	v_mov_b64_e32 v[30:31], v[10:11]
	v_add_f32_e32 v3, v3, v9
	v_add_f32_e32 v9, v2, v3
	v_mov_b32_e32 v2, v30
	v_mov_b32_e32 v3, v34
	v_mov_b32_e32 v4, v31
	v_mov_b32_e32 v5, v35
	v_pk_add_f32 v[2:3], v[2:3], v[4:5]
	v_mov_b32_e32 v4, v32
	v_mov_b32_e32 v5, v36
	v_pk_add_f32 v[2:3], v[4:5], v[2:3]
	v_mov_b32_e32 v4, v33
	v_mov_b32_e32 v5, v37
	v_pk_add_f32 v[2:3], v[4:5], v[2:3]
	v_add_u32_e32 v7, 0xffff8000, v6
	v_add_f32_e32 v3, v3, v9
	v_add_f32_e32 v4, v2, v3
	v_mov_b32_e32 v5, v4
	s_nop 1
	v_permlane32_swap_b32_e32 v5, v4
	v_cmp_gt_i32_e64 s[4:5], s22, v6
	v_ashrrev_i32_e32 v8, 31, v6
	s_waitcnt lgkmcnt(0)
	v_add_f32_e32 v4, v4, v5
	v_cndmask_b32_e64 v2, v7, v6, s[4:5]
	v_mov_b32_e32 v7, v4
	s_nop 1
	v_permlane16_swap_b32_e32 v7, v4
	v_mov_b32_e32 v6, s24
	v_mov_b32_e32 v5, s9
	v_cndmask_b32_e64 v3, 0, v8, s[4:5]
	v_cndmask_b32_e64 v5, v6, v5, s[4:5]
	s_waitcnt lgkmcnt(0)
	v_add_f32_e32 v7, v4, v7
	s_nop 1
	v_mov_b32_dpp v9, v7 row_ror:8 row_mask:0xf bank_mask:0xf
	v_mov_b32_e32 v6, s23
	v_mov_b32_e32 v8, s8
	v_cndmask_b32_e64 v4, v6, v8, s[4:5]
	v_lshlrev_b64 v[2:3], 13, v[2:3]
	s_waitcnt lgkmcnt(0)
	v_add_f32_e32 v12, v7, v9
	s_nop 1
	v_mov_b32_dpp v13, v12 row_ror:4 row_mask:0xf bank_mask:0xf
	v_lshl_add_u64 v[2:3], v[4:5], 0, v[2:3]
	v_lshl_add_u64 v[10:11], v[2:3], 0, v[66:67]
	v_add_co_u32_e64 v106, s[4:5], s25, v10
	s_waitcnt lgkmcnt(0)
	v_add_f32_e32 v12, v12, v13
	s_nop 1
	v_mov_b32_dpp v13, v12 row_ror:2 row_mask:0xf bank_mask:0xf
	v_addc_co_u32_e64 v107, s[4:5], 0, v11, s[4:5]
	global_load_dwordx4 v[42:45], v[10:11], off
	global_load_dwordx4 v[14:17], v[10:11], off offset:1024
	global_load_dwordx4 v[6:9], v[10:11], off offset:2048
	global_load_dwordx4 v[2:5], v[10:11], off offset:3072
	v_cmp_lt_i32_e64 s[4:5], s26, v117
	s_waitcnt lgkmcnt(0)
	v_add_f32_e32 v89, v12, v13
	global_load_dwordx4 v[26:29], v[106:107], off
	global_load_dwordx4 v[22:25], v[106:107], off offset:1024
	global_load_dwordx4 v[18:21], v[106:107], off offset:2048
	global_load_dwordx4 v[10:13], v[106:107], off offset:3072
	s_nop 1
	v_mov_b32_dpp v93, v89 row_ror:1 row_mask:0xf bank_mask:0xf
	s_waitcnt lgkmcnt(0)
	v_add_f32_e32 v89, v89, v93
	v_fmamk_f32 v51, v89, 0xba000000, v51
	v_fmamk_f32 v63, v89, 0xba000000, v63
	v_fmamk_f32 v111, v89, 0xba000000, v53
	v_fmamk_f32 v110, v89, 0xba000000, v52
	v_fmac_f32_e32 v50, 0xba000000, v89
	v_mul_f32_e32 v52, v51, v51
	v_fmac_f32_e32 v62, 0xba000000, v89
	v_mul_f32_e32 v53, v63, v63
	v_fmac_f32_e32 v52, v50, v50
	v_fmamk_f32 v108, v89, 0xba000000, v64
	v_fmac_f32_e32 v53, v62, v62
	v_fmac_f32_e32 v52, v110, v110
	v_fmamk_f32 v109, v89, 0xba000000, v65
	v_fmac_f32_e32 v53, v108, v108
	v_fmac_f32_e32 v52, v111, v111
	v_fmac_f32_e32 v53, v109, v109
	v_fmamk_f32 v59, v89, 0xba000000, v59
	v_add_f32_e32 v52, v52, v53
	v_fmac_f32_e32 v58, 0xba000000, v89
	v_mul_f32_e32 v53, v59, v59
	v_fmamk_f32 v106, v89, 0xba000000, v60
	v_fmac_f32_e32 v53, v58, v58
	v_fmamk_f32 v107, v89, 0xba000000, v61
	v_fmac_f32_e32 v53, v106, v106
	v_fmac_f32_e32 v53, v107, v107
	v_fmamk_f32 v55, v89, 0xba000000, v55
	v_add_f32_e32 v52, v53, v52
	v_fmac_f32_e32 v54, 0xba000000, v89
	v_mul_f32_e32 v53, v55, v55
	v_fmamk_f32 v64, v89, 0xba000000, v56
	v_fmac_f32_e32 v53, v54, v54
	v_fmamk_f32 v65, v89, 0xba000000, v57
	v_fmac_f32_e32 v53, v64, v64
	v_fmac_f32_e32 v53, v65, v65
	v_fmamk_f32 v61, v89, 0xba000000, v47
	v_fmac_f32_e32 v46, 0xba000000, v89
	v_fmamk_f32 v60, v89, 0xba000000, v39
	v_add_f32_e32 v93, v53, v52
	v_fmamk_f32 v56, v89, 0xba000000, v41
	v_fmamk_f32 v52, v89, 0xba000000, v40
	v_fmac_f32_e32 v38, 0xba000000, v89
	v_mov_b32_e32 v39, v46
	v_pk_mul_f32 v[40:41], v[60:61], v[60:61]
	v_fmamk_f32 v53, v89, 0xba000000, v48
	v_pk_fma_f32 v[40:41], v[38:39], v[38:39], v[40:41]
	v_fmamk_f32 v57, v89, 0xba000000, v49
	v_pk_fma_f32 v[40:41], v[52:53], v[52:53], v[40:41]
	v_fmamk_f32 v49, v89, 0xba000000, v35
	v_pk_fma_f32 v[40:41], v[56:57], v[56:57], v[40:41]
	v_fmac_f32_e32 v34, 0xba000000, v89
	v_add_f32_e32 v39, v41, v93
	v_fmamk_f32 v48, v89, 0xba000000, v31
	v_add_f32_e32 v39, v40, v39
	v_fmamk_f32 v41, v89, 0xba000000, v37
	v_fmamk_f32 v37, v89, 0xba000000, v36
	v_fmamk_f32 v40, v89, 0xba000000, v33
	v_fmamk_f32 v36, v89, 0xba000000, v32
	v_fmac_f32_e32 v30, 0xba000000, v89
	v_mov_b32_e32 v31, v34
	v_pk_mul_f32 v[32:33], v[48:49], v[48:49]
	s_nop 0
	v_pk_fma_f32 v[32:33], v[30:31], v[30:31], v[32:33]
	s_nop 0
	v_pk_fma_f32 v[32:33], v[36:37], v[36:37], v[32:33]
	s_nop 0
	v_pk_fma_f32 v[32:33], v[40:41], v[40:41], v[32:33]
	s_nop 0
	v_add_f32_e32 v31, v33, v39
	v_add_f32_e32 v31, v32, v31
	v_mov_b32_e32 v32, v31
	s_nop 1
	v_permlane32_swap_b32_e32 v32, v31
	s_waitcnt lgkmcnt(0)
	v_add_f32_e32 v31, v31, v32
	v_mov_b32_e32 v32, v31
	s_nop 1
	v_permlane16_swap_b32_e32 v32, v31
	s_waitcnt lgkmcnt(0)
	v_add_f32_e32 v31, v31, v32
	s_nop 1
	v_mov_b32_dpp v32, v31 row_ror:8 row_mask:0xf bank_mask:0xf
	s_waitcnt lgkmcnt(0)
	v_add_f32_e32 v31, v31, v32
	s_nop 1
	v_mov_b32_dpp v32, v31 row_ror:4 row_mask:0xf bank_mask:0xf
	s_waitcnt lgkmcnt(0)
	v_add_f32_e32 v31, v31, v32
	s_nop 1
	v_mov_b32_dpp v32, v31 row_ror:2 row_mask:0xf bank_mask:0xf
	s_waitcnt lgkmcnt(0)
	v_add_f32_e32 v31, v31, v32
	s_nop 1
	v_mov_b32_dpp v32, v31 row_ror:1 row_mask:0xf bank_mask:0xf
	s_waitcnt lgkmcnt(0)
	v_add_f32_e32 v31, v31, v32
	v_fmamk_f32 v31, v31, 0x3a000000, v118
	v_mul_f32_e32 v32, 0x4b800000, v31
	v_cmp_gt_f32_e64 s[6:7], s28, v31
	s_nop 1
	v_cndmask_b32_e64 v31, v31, v32, s[6:7]
	v_rsq_f32_e32 v31, v31
	s_nop 0
	v_mul_f32_e32 v32, 0x45800000, v31
	v_cndmask_b32_e64 v32, v31, v32, s[6:7]
	s_and_saveexec_b64 s[6:7], vcc
	s_cbranch_execz .LBB0_941
; DI void phase_norm(const Params& p, int mode, int l, int row_lo, int nrows, int bid, int nb) {
;     ...
;             if (mode == 1 && lane == 0) { stats[2 * r] = mu; stats[2 * r + 1] = rs; }
	v_mul_f32_e32 v122, 0x3a000000, v89
	v_ashrrev_i32_e32 v89, 31, v88
	v_lshl_add_u64 v[124:125], v[88:89], 2, s[20:21]
	v_mov_b32_e32 v123, v32
	global_store_dwordx2 v[124:125], v[122:123], off
	s_branch .LBB0_941

; DI void phase_norm(const Params& p, int mode, int l, int row_lo, int nrows, int bid, int nb) {
;     ...
;         { const int rn = r + nw < nrows ? r + nw : r;
;           const float* srcn = mode == 0 ? xin_row(p, rn) : (const float*)vrow(p, rn);
; #pragma unroll
;           for (int i = 0; i < 8; ++i) vn[i] = *(const f32x4*)(srcn + i * 256 + lane * 4); }
;         if (mode != 0) {
;             float s = 0.f;
; #pragma unroll
;             for (int i = 0; i < 8; ++i) s += v[i][0] + v[i][1] + v[i][2] + v[i][3];
;             s = wave_sum(s); const float mu = s * (1.f / 2048.f);
;             float q = 0.f;
; #pragma unroll
;             for (int i = 0; i < 8; ++i) { const f32x4 d = v[i] - mu; q += d[0] * d[0] + d[1] * d[1] + d[2] * d[2] + d[3] * d[3]; }
;             q = wave_sum(q); const float rs = rsqrtf(q * (1.f / 2048.f) + LN_EPS);
;             if (mode == 1 && lane == 0) { stats[2 * r] = mu; stats[2 * r + 1] = rs; }
.LBB0_1369:
	v_mov_b64_e32 v[64:65], v[24:25]
	v_mov_b64_e32 v[62:63], v[22:23]
	v_mov_b64_e32 v[60:61], v[16:17]
	v_mov_b64_e32 v[52:53], v[4:5]
	v_mov_b64_e32 v[58:59], v[14:15]
	v_mov_b64_e32 v[50:51], v[2:3]
	v_add_f32_e32 v2, v62, v63
	v_add_f32_e32 v2, v64, v2
	v_add_f32_e32 v3, v58, v59
	v_mov_b64_e32 v[56:57], v[8:9]
	v_add_f32_e32 v2, v65, v2
	v_add_f32_e32 v3, v60, v3
	v_mov_b64_e32 v[54:55], v[6:7]
	v_add_f32_e32 v2, 0, v2
	v_add_f32_e32 v3, v61, v3
	v_add_f32_e32 v2, v3, v2
	v_add_f32_e32 v3, v54, v55
	v_add_f32_e32 v3, v56, v3
	v_add_f32_e32 v3, v57, v3
	v_add_f32_e32 v2, v3, v2
	v_add_f32_e32 v3, v50, v51
	v_mov_b64_e32 v[48:49], v[32:33]
	v_mov_b64_e32 v[44:45], v[28:29]
	v_add_f32_e32 v3, v52, v3
	v_mov_b64_e32 v[46:47], v[30:31]
	v_mov_b64_e32 v[42:43], v[26:27]
	v_add_f32_e32 v3, v53, v3
	v_add_f32_e32 v9, v3, v2
	v_mov_b32_e32 v2, v42
	v_mov_b32_e32 v3, v46
	v_mov_b32_e32 v4, v43
	v_mov_b32_e32 v5, v47
	v_pk_add_f32 v[2:3], v[2:3], v[4:5]
	v_mov_b32_e32 v4, v44
	v_mov_b32_e32 v5, v48
	v_pk_add_f32 v[2:3], v[4:5], v[2:3]
	v_mov_b32_e32 v4, v45
	v_mov_b32_e32 v5, v49
	v_mov_b64_e32 v[40:41], v[20:21]
	v_mov_b64_e32 v[36:37], v[12:13]
	v_pk_add_f32 v[2:3], v[4:5], v[2:3]
	v_mov_b64_e32 v[38:39], v[18:19]
	v_mov_b64_e32 v[34:35], v[10:11]
	v_add_f32_e32 v3, v3, v9
	v_add_f32_e32 v9, v2, v3
	v_mov_b32_e32 v2, v34
	v_mov_b32_e32 v3, v38
	v_mov_b32_e32 v4, v35
	v_mov_b32_e32 v5, v39
	v_pk_add_f32 v[2:3], v[2:3], v[4:5]
	v_mov_b32_e32 v4, v36
	v_mov_b32_e32 v5, v40
	v_pk_add_f32 v[2:3], v[4:5], v[2:3]
	v_mov_b32_e32 v4, v37
	v_mov_b32_e32 v5, v41
	v_pk_add_f32 v[2:3], v[4:5], v[2:3]
	v_add_u32_e32 v122, s20, v106
	v_add_f32_e32 v3, v3, v9
	v_add_f32_e32 v4, v2, v3
	v_mov_b32_e32 v5, v4
	s_nop 1
	v_permlane32_swap_b32_e32 v5, v4
	v_cmp_gt_i32_e64 s[4:5], s26, v122
	s_waitcnt lgkmcnt(0)
	v_add_f32_e32 v4, v4, v5
	v_cndmask_b32_e64 v6, v106, v122, s[4:5]
	v_add_u32_e32 v7, 0xffff8000, v6
	v_cmp_gt_i32_e64 s[4:5], s27, v6
	v_ashrrev_i32_e32 v8, 31, v6
	v_mov_b32_e32 v5, s9
	v_cndmask_b32_e64 v2, v7, v6, s[4:5]
	v_mov_b32_e32 v7, v4
	s_nop 1
	v_permlane16_swap_b32_e32 v7, v4
	v_mov_b32_e32 v6, s29
	v_cndmask_b32_e64 v3, 0, v8, s[4:5]
	v_cndmask_b32_e64 v5, v6, v5, s[4:5]
	v_mov_b32_e32 v6, s28
	s_waitcnt lgkmcnt(0)
	v_add_f32_e32 v7, v4, v7
	s_nop 1
	v_mov_b32_dpp v9, v7 row_ror:8 row_mask:0xf bank_mask:0xf
	v_mov_b32_e32 v8, s8
	v_cndmask_b32_e64 v4, v6, v8, s[4:5]
	v_lshlrev_b64 v[2:3], 13, v[2:3]
	v_lshl_add_u64 v[2:3], v[4:5], 0, v[2:3]
	s_waitcnt lgkmcnt(0)
	v_add_f32_e32 v12, v7, v9
	s_nop 1
	v_mov_b32_dpp v13, v12 row_ror:4 row_mask:0xf bank_mask:0xf
	v_lshl_add_u64 v[10:11], v[2:3], 0, v[66:67]
	v_add_co_u32_e64 v108, s[4:5], s30, v10
	global_load_dwordx4 v[22:25], v[10:11], off
	global_load_dwordx4 v[14:17], v[10:11], off offset:1024
	global_load_dwordx4 v[6:9], v[10:11], off offset:2048
	global_load_dwordx4 v[2:5], v[10:11], off offset:3072
	s_waitcnt lgkmcnt(0)
	v_add_f32_e32 v12, v12, v13
	s_nop 1
	v_mov_b32_dpp v13, v12 row_ror:2 row_mask:0xf bank_mask:0xf
	v_addc_co_u32_e64 v109, s[4:5], 0, v11, s[4:5]
	v_cmp_lt_i32_e64 s[4:5], s21, v122
	s_waitcnt lgkmcnt(0)
	v_add_f32_e32 v89, v12, v13
	global_load_dwordx4 v[30:33], v[108:109], off
	global_load_dwordx4 v[26:29], v[108:109], off offset:1024
	global_load_dwordx4 v[18:21], v[108:109], off offset:2048
	global_load_dwordx4 v[10:13], v[108:109], off offset:3072
	s_nop 1
	v_mov_b32_dpp v93, v89 row_ror:1 row_mask:0xf bank_mask:0xf
	s_waitcnt lgkmcnt(0)
	v_add_f32_e32 v89, v89, v93
	v_fmamk_f32 v63, v89, 0xba000000, v63
	v_fmamk_f32 v59, v89, 0xba000000, v59
	v_fmamk_f32 v112, v89, 0xba000000, v64
	v_fmac_f32_e32 v62, 0xba000000, v89
	v_mul_f32_e32 v64, v63, v63
	v_fmamk_f32 v110, v89, 0xba000000, v60
	v_fmac_f32_e32 v58, 0xba000000, v89
	v_mul_f32_e32 v60, v59, v59
	v_fmac_f32_e32 v64, v62, v62
	v_fmac_f32_e32 v60, v58, v58
	v_fmamk_f32 v113, v89, 0xba000000, v65
	v_fmac_f32_e32 v64, v112, v112
	v_fmamk_f32 v111, v89, 0xba000000, v61
	v_fmac_f32_e32 v60, v110, v110
	v_fmamk_f32 v55, v89, 0xba000000, v55
	v_fmac_f32_e32 v64, v113, v113
	v_fmac_f32_e32 v60, v111, v111
	v_fmamk_f32 v108, v89, 0xba000000, v56
	v_fmac_f32_e32 v54, 0xba000000, v89
	v_mul_f32_e32 v56, v55, v55
	v_fmamk_f32 v51, v89, 0xba000000, v51
	v_add_f32_e32 v60, v64, v60
	v_fmac_f32_e32 v56, v54, v54
	v_fmamk_f32 v64, v89, 0xba000000, v52
	v_fmac_f32_e32 v50, 0xba000000, v89
	v_mul_f32_e32 v52, v51, v51
	v_fmamk_f32 v109, v89, 0xba000000, v57
	v_fmac_f32_e32 v56, v108, v108
	v_fmac_f32_e32 v52, v50, v50
	v_fmac_f32_e32 v56, v109, v109
	v_fmamk_f32 v65, v89, 0xba000000, v53
	v_fmac_f32_e32 v52, v64, v64
	v_add_f32_e32 v56, v56, v60
	v_fmac_f32_e32 v52, v65, v65
	v_fmamk_f32 v61, v89, 0xba000000, v47
	v_fmac_f32_e32 v46, 0xba000000, v89
	v_fmamk_f32 v60, v89, 0xba000000, v43
	v_add_f32_e32 v93, v52, v56
	v_fmamk_f32 v56, v89, 0xba000000, v45
	v_fmamk_f32 v52, v89, 0xba000000, v44
	v_fmac_f32_e32 v42, 0xba000000, v89
	v_mov_b32_e32 v43, v46
	v_pk_mul_f32 v[44:45], v[60:61], v[60:61]
	v_fmamk_f32 v53, v89, 0xba000000, v48
	v_pk_fma_f32 v[44:45], v[42:43], v[42:43], v[44:45]
	v_fmamk_f32 v57, v89, 0xba000000, v49
	v_pk_fma_f32 v[44:45], v[52:53], v[52:53], v[44:45]
	v_fmamk_f32 v49, v89, 0xba000000, v39
	v_pk_fma_f32 v[44:45], v[56:57], v[56:57], v[44:45]
	v_fmac_f32_e32 v38, 0xba000000, v89
	v_add_f32_e32 v43, v45, v93
	v_fmamk_f32 v48, v89, 0xba000000, v35
	v_add_f32_e32 v43, v44, v43
	v_fmamk_f32 v45, v89, 0xba000000, v41
	v_fmamk_f32 v41, v89, 0xba000000, v40
	v_fmamk_f32 v44, v89, 0xba000000, v37
	v_fmamk_f32 v40, v89, 0xba000000, v36
	v_fmac_f32_e32 v34, 0xba000000, v89
	v_mov_b32_e32 v35, v38
	v_pk_mul_f32 v[36:37], v[48:49], v[48:49]
	s_nop 0
	v_pk_fma_f32 v[36:37], v[34:35], v[34:35], v[36:37]
	s_nop 0
	v_pk_fma_f32 v[36:37], v[40:41], v[40:41], v[36:37]
	s_nop 0
	v_pk_fma_f32 v[36:37], v[44:45], v[44:45], v[36:37]
	s_nop 0
	v_add_f32_e32 v35, v37, v43
	v_add_f32_e32 v35, v36, v35
	v_mov_b32_e32 v36, v35
	s_nop 1
	v_permlane32_swap_b32_e32 v36, v35
	s_waitcnt lgkmcnt(0)
	v_add_f32_e32 v35, v35, v36
	v_mov_b32_e32 v36, v35
	s_nop 1
	v_permlane16_swap_b32_e32 v36, v35
	s_waitcnt lgkmcnt(0)
	v_add_f32_e32 v35, v35, v36
	s_nop 1
	v_mov_b32_dpp v36, v35 row_ror:8 row_mask:0xf bank_mask:0xf
	s_waitcnt lgkmcnt(0)
	v_add_f32_e32 v35, v35, v36
	s_nop 1
	v_mov_b32_dpp v36, v35 row_ror:4 row_mask:0xf bank_mask:0xf
	s_waitcnt lgkmcnt(0)
	v_add_f32_e32 v35, v35, v36
	s_nop 1
	v_mov_b32_dpp v36, v35 row_ror:2 row_mask:0xf bank_mask:0xf
	s_waitcnt lgkmcnt(0)
	v_add_f32_e32 v35, v35, v36
	s_nop 1
	v_mov_b32_dpp v36, v35 row_ror:1 row_mask:0xf bank_mask:0xf
	s_waitcnt lgkmcnt(0)
	v_add_f32_e32 v35, v35, v36
	v_fmamk_f32 v35, v35, 0x3a000000, v107
	v_mul_f32_e32 v36, 0x4b800000, v35
	v_cmp_gt_f32_e64 s[6:7], s33, v35
	s_nop 1
	v_cndmask_b32_e64 v35, v35, v36, s[6:7]
	v_rsq_f32_e32 v35, v35
	s_nop 0
	v_mul_f32_e32 v36, 0x45800000, v35
	v_cndmask_b32_e64 v36, v35, v36, s[6:7]
	s_and_saveexec_b64 s[6:7], vcc
	s_cbranch_execz .LBB0_1368
; DI void phase_norm(const Params& p, int mode, int l, int row_lo, int nrows, int bid, int nb) {
;     ...
;             if (mode == 1 && lane == 0) { stats[2 * r] = mu; stats[2 * r + 1] = rs; }
	v_mul_f32_e32 v124, 0x3a000000, v89
	v_ashrrev_i32_e32 v89, 31, v88
	v_lshl_add_u64 v[126:127], v[88:89], 2, s[22:23]
	v_mov_b32_e32 v125, v36
	global_store_dwordx2 v[126:127], v[124:125], off
	s_branch .LBB0_1368

; DI float lo_bf(unsigned u) { return __uint_as_float(u << 16); }
; DI float hi_bf(unsigned u) { return __uint_as_float(u & 0xffff0000u); }
; DI void phase_mix_gla(const Params& p, int j, int row_lo, int nrows, int bid, int nb) {
;     ...
;             const u32x4 gq0 = *(const u32x4*)(row + 6144 + c0), gq1 = *(const u32x4*)(row + 6144 + c0 + 8);
; #pragma unroll
;             for (int q = 0; q < 2; ++q) { const u32x4 a = *(const u32x4*)(row + c0 + 8 * q), b = *(const u32x4*)(row + 2048 + c0 + 8 * q);
;                 o[8 * q + 0] = lo_bf(a.x) + lo_bf(b.x); o[8 * q + 1] = hi_bf(a.x) + hi_bf(b.x); o[8 * q + 2] = lo_bf(a.y) + lo_bf(b.y); o[8 * q + 3] = hi_bf(a.y) + hi_bf(b.y);
;                 o[8 * q + 4] = lo_bf(a.z) + lo_bf(b.z); o[8 * q + 5] = hi_bf(a.z) + hi_bf(b.z); o[8 * q + 6] = lo_bf(a.w) + lo_bf(b.w); o[8 * q + 7] = hi_bf(a.w) + hi_bf(b.w); }
;             float ss = 0.f;
; #pragma unroll
;             for (int i = 0; i < 16; ++i) ss += o[i] * o[i];
; #pragma unroll
;             for (int m = 8; m > 0; m >>= 1) ss += __shfl_xor(ss, m);
;             const float rs = rsqrtf(ss * (1.f / 256.f) + LN_EPS);
.LBB0_1885:
	v_lshl_add_u64 v[2:3], v[28:29], 0, s[16:17]
	global_load_dwordx4 v[22:25], v[28:29], off offset:-16
	global_load_dwordx4 v[14:17], v[2:3], off offset:16
	v_lshl_add_u64 v[2:3], v[28:29], 0, s[18:19]
	global_load_dwordx4 v[18:21], v[2:3], off offset:16
	v_add_co_u32_e32 v2, vcc, 0xffffd000, v28
	v_add_u32_e32 v1, s20, v1
	s_nop 0
	v_addc_co_u32_e32 v3, vcc, -1, v29, vcc
	global_load_dwordx4 v[56:59], v[2:3], off offset:-16
	v_add_co_u32_e32 v30, vcc, 0xffffe000, v28
	s_waitcnt vmcnt(3)
	v_lshlrev_b32_e32 v55, 16, v24
	v_addc_co_u32_e32 v31, vcc, -1, v29, vcc
	global_load_dwordx4 v[60:63], v[30:31], off offset:-16
	global_load_dwordx4 v[2:5], v[28:29], off
	global_load_dwordx4 v[6:9], v[26:27], off offset:1040
	global_load_dwordx4 v[10:13], v[26:27], off offset:1024
	v_and_b32_e32 v24, 0xffff0000, v24
	s_waitcnt vmcnt(6)
	v_and_b32_e32 v30, 0xffff0000, v17
	v_lshlrev_b32_e32 v31, 16, v17
	s_waitcnt vmcnt(5)
	v_and_b32_e32 v32, 0xffff0000, v21
	v_lshlrev_b32_e32 v33, 16, v21
	v_mul_f32_e32 v17, 0xbfb8aa3b, v55
	v_mul_f32_e32 v21, 0xbfb8aa3b, v24
	v_lshlrev_b32_e32 v64, 16, v23
	v_and_b32_e32 v23, 0xffff0000, v23
	v_exp_f32_e32 v40, v17
	v_exp_f32_e32 v41, v21
	v_mul_f32_e32 v38, 0xbfb8aa3b, v64
	v_mul_f32_e32 v39, 0xbfb8aa3b, v23
	v_exp_f32_e32 v48, v38
	v_exp_f32_e32 v49, v39
	v_pk_add_f32 v[40:41], v[40:41], 1.0 op_sel_hi:[1,0]
	s_waitcnt vmcnt(4)
	v_lshlrev_b32_e32 v36, 16, v57
	v_div_scale_f32 v17, s[4:5], v41, v41, v24
	v_and_b32_e32 v37, 0xffff0000, v57
	v_pk_add_f32 v[48:49], v[48:49], 1.0 op_sel_hi:[1,0]
	v_div_scale_f32 v57, s[4:5], v40, v40, v55
	v_pk_add_f32 v[30:31], v[30:31], v[32:33]
	v_lshlrev_b32_e32 v32, 16, v59
	v_and_b32_e32 v33, 0xffff0000, v59
	v_div_scale_f32 v59, s[6:7], v49, v49, v23
	v_rcp_f32_e32 v65, v57
	v_rcp_f32_e32 v66, v59
	v_div_scale_f32 v21, vcc, v24, v41, v24
	v_fma_f32 v69, -v57, v65, 1.0
	v_lshlrev_b32_e32 v34, 16, v58
	v_and_b32_e32 v35, 0xffff0000, v58
	v_div_scale_f32 v58, s[4:5], v55, v40, v55
	v_fma_f32 v70, -v59, v66, 1.0
	v_fmac_f32_e32 v65, v69, v65
	v_fmac_f32_e32 v66, v70, v66
	v_mul_f32_e32 v69, v58, v65
	v_fma_f32 v72, -v57, v69, v58
	v_fmac_f32_e32 v69, v72, v65
	v_pk_mul_f32 v[38:39], v[30:31], v[30:31]
	s_waitcnt vmcnt(3)
	v_lshlrev_b32_e32 v42, 16, v63
	v_and_b32_e32 v43, 0xffff0000, v63
	v_rcp_f32_e32 v63, v17
	v_lshlrev_b32_e32 v46, 16, v61
	v_and_b32_e32 v47, 0xffff0000, v61
	v_div_scale_f32 v61, s[6:7], v23, v49, v23
	v_fma_f32 v68, -v17, v63, 1.0
	v_fmac_f32_e32 v63, v68, v63
	v_mul_f32_e32 v68, v21, v63
	v_fma_f32 v71, -v17, v68, v21
	v_lshlrev_b32_e32 v44, 16, v62
	v_and_b32_e32 v45, 0xffff0000, v62
	v_div_scale_f32 v62, s[24:25], v48, v48, v64
	v_mul_f32_e32 v70, v61, v66
	v_fmac_f32_e32 v68, v71, v63
	v_rcp_f32_e32 v67, v62
	v_fma_f32 v73, -v59, v70, v61
	v_fma_f32 v17, -v17, v68, v21
	v_fmac_f32_e32 v70, v73, v66
	v_fma_f32 v21, -v57, v69, v58
	v_div_fmas_f32 v17, v17, v63, v68
	s_mov_b64 vcc, s[4:5]
	v_fma_f32 v57, -v59, v70, v61
	v_div_fixup_f32 v41, v17, v41, v24
	v_div_fmas_f32 v17, v21, v65, v69
	s_mov_b64 vcc, s[6:7]
	v_div_fixup_f32 v40, v17, v40, v55
	v_div_fmas_f32 v17, v57, v66, v70
	v_div_fixup_f32 v49, v17, v49, v23
	v_fma_f32 v17, -v62, v67, 1.0
	v_fmac_f32_e32 v67, v17, v67
	v_div_scale_f32 v17, vcc, v64, v48, v64
	v_mul_f32_e32 v21, v17, v67
	v_fma_f32 v23, -v62, v21, v17
	v_fmac_f32_e32 v21, v23, v67
	v_fma_f32 v17, -v62, v21, v17
	v_div_fmas_f32 v17, v17, v67, v21
	v_div_fixup_f32 v48, v17, v48, v64
	v_lshlrev_b32_e32 v17, 16, v22
	v_and_b32_e32 v21, 0xffff0000, v22
	v_mul_f32_e32 v22, 0xbfb8aa3b, v17
	v_mul_f32_e32 v23, 0xbfb8aa3b, v21
	v_exp_f32_e32 v22, v22
	v_exp_f32_e32 v23, v23
	v_lshlrev_b32_e32 v58, 16, v56
	v_and_b32_e32 v59, 0xffff0000, v56
	v_lshlrev_b32_e32 v56, 16, v60
	v_pk_add_f32 v[22:23], v[22:23], 1.0 op_sel_hi:[1,0]
	v_and_b32_e32 v57, 0xffff0000, v60
	v_div_scale_f32 v24, s[4:5], v23, v23, v21
	v_rcp_f32_e32 v55, v24
	v_lshlrev_b32_e32 v66, 16, v25
	v_and_b32_e32 v67, 0xffff0000, v25
	v_mul_f32_e32 v25, 0xbfb8aa3b, v67
	v_fma_f32 v60, -v24, v55, 1.0
	v_fmac_f32_e32 v55, v60, v55
	v_div_scale_f32 v60, vcc, v21, v23, v21
	v_mul_f32_e32 v61, v60, v55
	v_fma_f32 v62, -v24, v61, v60
	v_fmac_f32_e32 v61, v62, v55
	v_fma_f32 v24, -v24, v61, v60
	v_div_scale_f32 v60, s[4:5], v22, v22, v17
	v_div_fmas_f32 v24, v24, v55, v61
	v_rcp_f32_e32 v62, v60
	v_div_fixup_f32 v23, v24, v23, v21
	v_mul_f32_e32 v24, 0xbfb8aa3b, v66
	v_exp_f32_e32 v24, v24
	v_exp_f32_e32 v25, v25
	v_fma_f32 v21, -v60, v62, 1.0
	v_fmac_f32_e32 v62, v21, v62
	v_div_scale_f32 v21, vcc, v17, v22, v17
	v_pk_add_f32 v[24:25], v[24:25], 1.0 op_sel_hi:[1,0]
	v_mul_f32_e32 v55, v21, v62
	v_div_scale_f32 v68, s[4:5], v25, v25, v67
	v_pk_add_f32 v[56:57], v[58:59], v[56:57]
	v_fma_f32 v61, -v60, v55, v21
	v_rcp_f32_e32 v69, v68
	v_pk_add_f32 v[36:37], v[36:37], v[46:47]
	v_pk_mul_f32 v[58:59], v[56:57], v[56:57]
	v_fmac_f32_e32 v55, v61, v62
	v_pk_mul_f32 v[46:47], v[36:37], v[36:37]
	v_fma_f32 v21, -v60, v55, v21
	v_add_f32_e32 v58, v58, v59
	v_pk_add_f32 v[34:35], v[34:35], v[44:45]
	v_div_fmas_f32 v21, v21, v62, v55
	v_add_f32_e32 v46, v46, v58
	v_pk_mul_f32 v[44:45], v[34:35], v[34:35]
	v_div_fixup_f32 v22, v21, v22, v17
	v_fma_f32 v17, -v68, v69, 1.0
	v_add_f32_e32 v46, v47, v46
	v_pk_add_f32 v[32:33], v[32:33], v[42:43]
	v_fmac_f32_e32 v69, v17, v69
	v_lshlrev_b32_e32 v60, 16, v16
	v_and_b32_e32 v61, 0xffff0000, v16
	v_lshlrev_b32_e32 v16, 16, v20
	v_and_b32_e32 v17, 0xffff0000, v20
	v_add_f32_e32 v44, v44, v46
	v_pk_mul_f32 v[42:43], v[32:33], v[32:33]
	v_pk_add_f32 v[16:17], v[60:61], v[16:17]
	v_lshlrev_b32_e32 v60, 16, v15
	v_and_b32_e32 v61, 0xffff0000, v15
	v_lshlrev_b32_e32 v64, 16, v14
	v_and_b32_e32 v65, 0xffff0000, v14
	v_lshlrev_b32_e32 v14, 16, v18
	v_and_b32_e32 v15, 0xffff0000, v18
	v_add_f32_e32 v44, v45, v44
	v_pk_add_f32 v[14:15], v[64:65], v[14:15]
	v_add_f32_e32 v42, v42, v44
	v_lshlrev_b32_e32 v62, 16, v19
	v_and_b32_e32 v63, 0xffff0000, v19
	v_pk_mul_f32 v[18:19], v[14:15], v[14:15]
	v_add_f32_e32 v42, v43, v42
	v_pk_add_f32 v[60:61], v[60:61], v[62:63]
	v_add_f32_e32 v18, v18, v42
	v_pk_mul_f32 v[62:63], v[60:61], v[60:61]
	v_add_f32_e32 v18, v19, v18
	v_add_f32_e32 v18, v62, v18
	v_pk_mul_f32 v[20:21], v[16:17], v[16:17]
	v_add_f32_e32 v18, v63, v18
	v_add_f32_e32 v18, v20, v18
	v_add_f32_e32 v18, v21, v18
	v_add_f32_e32 v18, v39, v18
	v_add_f32_e32 v18, v38, v18
	s_nop 1
	v_mov_b32_dpp v19, v18 row_ror:8 row_mask:0xf bank_mask:0xf
	v_div_scale_f32 v55, vcc, v67, v25, v67
	v_mul_f32_e32 v70, v55, v69
	v_fma_f32 v71, -v68, v70, v55
	s_waitcnt lgkmcnt(0)
; DI unsigned pk2(float lo, float hi) { f32x2 v = {lo, hi}; bfv2 b = __builtin_convertvector(v, bfv2); return __builtin_bit_cast(unsigned, b); }
; DI float lo_bf(unsigned u) { return __uint_as_float(u << 16); }
; DI float hi_bf(unsigned u) { return __uint_as_float(u & 0xffff0000u); }
; DI float silu(float x) { return x / (1.f + __expf(-x)); }
; DI void phase_mix_gla(const Params& p, int j, int row_lo, int nrows, int bid, int nb) {
;     ...
;             for (int m = 8; m > 0; m >>= 1) ss += __shfl_xor(ss, m);
;             const float rs = rsqrtf(ss * (1.f / 256.f) + LN_EPS);
;             const int vc = (lane & 15) * 16;
; #pragma unroll
;             for (int q = 0; q < 2; ++q) { const u32x4 gq = q ? gq1 : gq0;
;                 const f32x4 w0 = *(const f32x4*)(gnw + vc + 8 * q), w1 = *(const f32x4*)(gnw + vc + 8 * q + 4);
;                 u32x4 y;
;                 y.x = pk2(o[8 * q + 0] * rs * w0[0] * silu(lo_bf(gq.x)), o[8 * q + 1] * rs * w0[1] * silu(hi_bf(gq.x)));
;                 y.y = pk2(o[8 * q + 2] * rs * w0[2] * silu(lo_bf(gq.y)), o[8 * q + 3] * rs * w0[3] * silu(hi_bf(gq.y)));
;                 y.z = pk2(o[8 * q + 4] * rs * w1[0] * silu(lo_bf(gq.z)), o[8 * q + 5] * rs * w1[1] * silu(hi_bf(gq.z)));
;                 y.w = pk2(o[8 * q + 6] * rs * w1[2] * silu(lo_bf(gq.w)), o[8 * q + 7] * rs * w1[3] * silu(hi_bf(gq.w)));
;                 *(u32x4*)(row + 6144 + c0 + 8 * q) = y; }
	v_add_f32_e32 v18, v18, v19
	s_nop 1
	v_mov_b32_dpp v21, v18 row_ror:4 row_mask:0xf bank_mask:0xf
	v_fmac_f32_e32 v70, v71, v69
	v_fma_f32 v20, -v68, v70, v55
	v_div_fmas_f32 v20, v20, v69, v70
	v_div_fixup_f32 v19, v20, v25, v67
	s_waitcnt lgkmcnt(0)
	v_add_f32_e32 v18, v18, v21
	s_nop 1
	v_mov_b32_dpp v20, v18 row_ror:2 row_mask:0xf bank_mask:0xf
	v_div_scale_f32 v38, s[4:5], v24, v24, v66
	v_rcp_f32_e32 v39, v38
	s_waitcnt lgkmcnt(0)
	v_add_f32_e32 v18, v18, v20
	s_nop 1
	v_mov_b32_dpp v20, v18 row_ror:1 row_mask:0xf bank_mask:0xf
	v_fma_f32 v21, -v38, v39, 1.0
	v_fmac_f32_e32 v39, v21, v39
	v_div_scale_f32 v21, vcc, v66, v24, v66
	s_waitcnt lgkmcnt(0)
	v_add_f32_e32 v18, v18, v20
	v_fmamk_f32 v18, v18, 0x3b800000, v54
	v_mul_f32_e32 v20, 0x4b800000, v18
	v_cmp_gt_f32_e64 s[4:5], s21, v18
	v_mul_f32_e32 v25, v21, v39
	v_fma_f32 v42, -v38, v25, v21
	v_cndmask_b32_e64 v18, v18, v20, s[4:5]
	v_rsq_f32_e32 v20, v18
	v_fmac_f32_e32 v25, v42, v39
	v_fma_f32 v21, -v38, v25, v21
	v_div_fmas_f32 v18, v21, v39, v25
	v_mul_f32_e32 v21, 0x45800000, v20
	v_cndmask_b32_e64 v20, v20, v21, s[4:5]
	v_div_fixup_f32 v18, v18, v24, v66
	v_pk_mul_f32 v[24:25], v[56:57], v[20:21] op_sel_hi:[1,0]
	s_waitcnt vmcnt(0)
	v_pk_mul_f32 v[10:11], v[10:11], v[24:25]
	s_nop 0
	v_pk_mul_f32 v[10:11], v[22:23], v[10:11]
	v_pk_mul_f32 v[22:23], v[36:37], v[20:21] op_sel_hi:[1,0]
	v_cvt_pk_bf16_f32 v10, v10, v11
	v_pk_mul_f32 v[12:13], v[12:13], v[22:23]
	s_nop 0
	v_pk_mul_f32 v[12:13], v[48:49], v[12:13]
	s_nop 0
	v_cvt_pk_bf16_f32 v11, v12, v13
	v_pk_mul_f32 v[12:13], v[34:35], v[20:21] op_sel_hi:[1,0]
	s_nop 0
	v_pk_mul_f32 v[6:7], v[6:7], v[12:13]
	s_nop 0
	v_pk_mul_f32 v[6:7], v[40:41], v[6:7]
	s_nop 0
	v_cvt_pk_bf16_f32 v12, v6, v7
	v_pk_mul_f32 v[6:7], v[32:33], v[20:21] op_sel_hi:[1,0]
	v_lshlrev_b32_e32 v21, 16, v3
	v_pk_mul_f32 v[6:7], v[8:9], v[6:7]
	v_and_b32_e32 v3, 0xffff0000, v3
	v_pk_mul_f32 v[6:7], v[18:19], v[6:7]
	v_and_b32_e32 v33, 0xffff0000, v2
	v_cvt_pk_bf16_f32 v13, v6, v7
	global_store_dwordx4 v[28:29], v[10:13], off offset:-16
	global_load_dwordx4 v[6:9], v[26:27], off offset:1056
	s_nop 0
	v_mul_f32_e32 v10, 0xbfb8aa3b, v21
	v_mul_f32_e32 v11, 0xbfb8aa3b, v3
	v_exp_f32_e32 v10, v10
	v_exp_f32_e32 v11, v11
	s_nop 0
	v_pk_add_f32 v[18:19], v[10:11], 1.0 op_sel_hi:[1,0]
	global_load_dwordx4 v[10:13], v[26:27], off offset:1072
	v_div_scale_f32 v22, s[4:5], v19, v19, v3
	v_rcp_f32_e32 v23, v22
	s_nop 0
	v_fma_f32 v24, -v22, v23, 1.0
	v_fmac_f32_e32 v23, v24, v23
	v_div_scale_f32 v24, vcc, v3, v19, v3
	v_mul_f32_e32 v25, v24, v23
	v_fma_f32 v32, -v22, v25, v24
	v_fmac_f32_e32 v25, v32, v23
	v_fma_f32 v22, -v22, v25, v24
	v_div_scale_f32 v24, s[4:5], v18, v18, v21
	v_rcp_f32_e32 v32, v24
	v_div_fmas_f32 v22, v22, v23, v25
	v_div_fixup_f32 v19, v22, v19, v3
	v_lshlrev_b32_e32 v25, 16, v2
	v_fma_f32 v3, -v24, v32, 1.0
	v_fmac_f32_e32 v32, v3, v32
	v_mul_f32_e32 v2, 0xbfb8aa3b, v25
	v_mul_f32_e32 v3, 0xbfb8aa3b, v33
	v_exp_f32_e32 v2, v2
	v_exp_f32_e32 v3, v3
	v_div_scale_f32 v22, vcc, v21, v18, v21
	v_mul_f32_e32 v23, v22, v32
	v_fma_f32 v34, -v24, v23, v22
	v_fmac_f32_e32 v23, v34, v32
	v_pk_add_f32 v[2:3], v[2:3], 1.0 op_sel_hi:[1,0]
	v_fma_f32 v22, -v24, v23, v22
	v_div_scale_f32 v24, s[4:5], v3, v3, v33
	v_rcp_f32_e32 v34, v24
	v_div_fmas_f32 v22, v22, v32, v23
	v_div_fixup_f32 v18, v22, v18, v21
	v_fma_f32 v21, -v24, v34, 1.0
	v_fmac_f32_e32 v34, v21, v34
	v_div_scale_f32 v21, vcc, v33, v3, v33
	v_mul_f32_e32 v22, v21, v34
	v_fma_f32 v23, -v24, v22, v21
	v_fmac_f32_e32 v22, v23, v34
	v_div_scale_f32 v23, s[4:5], v2, v2, v25
	v_fma_f32 v21, -v24, v22, v21
	v_rcp_f32_e32 v24, v23
	v_div_fmas_f32 v21, v21, v34, v22
	v_div_fixup_f32 v3, v21, v3, v33
	v_fma_f32 v21, -v23, v24, 1.0
	v_fmac_f32_e32 v24, v21, v24
	v_div_scale_f32 v21, vcc, v25, v2, v25
	v_mul_f32_e32 v22, v21, v24
	v_fma_f32 v32, -v23, v22, v21
	v_fmac_f32_e32 v22, v32, v24
	v_fma_f32 v21, -v23, v22, v21
	v_div_fmas_f32 v21, v21, v24, v22
	v_pk_mul_f32 v[14:15], v[14:15], v[20:21] op_sel_hi:[1,0]
	v_div_fixup_f32 v2, v21, v2, v25
	v_lshlrev_b32_e32 v21, 16, v4
	v_and_b32_e32 v4, 0xffff0000, v4
	s_waitcnt vmcnt(1)
	v_pk_mul_f32 v[6:7], v[6:7], v[14:15]
	s_nop 0
	v_pk_mul_f32 v[2:3], v[2:3], v[6:7]
	v_pk_mul_f32 v[14:15], v[60:61], v[20:21] op_sel_hi:[1,0]
	v_cvt_pk_bf16_f32 v2, v2, v3
	v_mul_f32_e32 v3, 0xbfb8aa3b, v21
	v_exp_f32_e32 v6, v3
	v_mul_f32_e32 v3, 0xbfb8aa3b, v4
	v_exp_f32_e32 v7, v3
	v_pk_mul_f32 v[8:9], v[8:9], v[14:15]
	v_pk_add_f32 v[6:7], v[6:7], 1.0 op_sel_hi:[1,0]
	s_nop 0
	v_div_scale_f32 v14, s[4:5], v7, v7, v4
	v_rcp_f32_e32 v15, v14
	v_pk_mul_f32 v[8:9], v[18:19], v[8:9]
	s_nop 0
	v_cvt_pk_bf16_f32 v3, v8, v9
	v_pk_mul_f32 v[8:9], v[16:17], v[20:21] op_sel_hi:[1,0]
	s_waitcnt vmcnt(0)
	v_pk_mul_f32 v[8:9], v[10:11], v[8:9]
	v_fma_f32 v10, -v14, v15, 1.0
	v_fmac_f32_e32 v15, v10, v15
	v_div_scale_f32 v10, vcc, v4, v7, v4
	v_mul_f32_e32 v11, v10, v15
	v_fma_f32 v16, -v14, v11, v10
	v_fmac_f32_e32 v11, v16, v15
	v_fma_f32 v10, -v14, v11, v10
	v_div_scale_f32 v14, s[4:5], v6, v6, v21
	v_rcp_f32_e32 v16, v14
	v_div_fmas_f32 v10, v10, v15, v11
	v_div_fixup_f32 v7, v10, v7, v4
	v_and_b32_e32 v15, 0xffff0000, v5
	v_fma_f32 v4, -v14, v16, 1.0
	v_fmac_f32_e32 v16, v4, v16
	v_div_scale_f32 v4, vcc, v21, v6, v21
	v_mul_f32_e32 v10, v4, v16
	v_fma_f32 v11, -v14, v10, v4
	v_fmac_f32_e32 v10, v11, v16
	v_fma_f32 v11, -v14, v10, v4
	v_lshlrev_b32_e32 v14, 16, v5
	v_mul_f32_e32 v4, 0xbfb8aa3b, v14
	v_mul_f32_e32 v5, 0xbfb8aa3b, v15
	v_exp_f32_e32 v4, v4
	v_exp_f32_e32 v5, v5
	v_div_fmas_f32 v10, v11, v16, v10
	v_div_fixup_f32 v6, v10, v6, v21
	v_pk_mul_f32 v[6:7], v[6:7], v[8:9]
	v_pk_add_f32 v[8:9], v[4:5], 1.0 op_sel_hi:[1,0]
	v_cvt_pk_bf16_f32 v4, v6, v7
	v_div_scale_f32 v5, s[4:5], v9, v9, v15
	v_rcp_f32_e32 v10, v5
	v_pk_mul_f32 v[6:7], v[30:31], v[20:21] op_sel_hi:[1,0]
	v_fma_f32 v11, -v5, v10, 1.0
	v_fmac_f32_e32 v10, v11, v10
	v_div_scale_f32 v11, vcc, v15, v9, v15
	v_pk_mul_f32 v[6:7], v[12:13], v[6:7] op_sel:[0,1] op_sel_hi:[1,0]
	v_mul_f32_e32 v12, v11, v10
	v_fma_f32 v13, -v5, v12, v11
	v_fmac_f32_e32 v12, v13, v10
	v_fma_f32 v5, -v5, v12, v11
	v_div_scale_f32 v11, s[4:5], v8, v8, v14
	v_rcp_f32_e32 v13, v11
	v_div_fmas_f32 v5, v5, v10, v12
	v_div_fixup_f32 v9, v5, v9, v15
	v_fma_f32 v5, -v11, v13, 1.0
	v_fmac_f32_e32 v13, v5, v13
	v_div_scale_f32 v5, vcc, v14, v8, v14
	v_mul_f32_e32 v10, v5, v13
	v_fma_f32 v12, -v11, v10, v5
	v_fmac_f32_e32 v10, v12, v13
	v_fma_f32 v5, -v11, v10, v5
	v_div_fmas_f32 v5, v5, v13, v10
	v_div_fixup_f32 v8, v5, v8, v14
	v_pk_mul_f32 v[6:7], v[8:9], v[6:7]
	v_cmp_lt_i32_e32 vcc, s22, v1
	v_cvt_pk_bf16_f32 v5, v6, v7
	global_store_dwordx4 v[28:29], v[2:5], off
	s_or_b64 s[14:15], vcc, s[14:15]
	v_lshl_add_u64 v[28:29], v[28:29], 0, s[12:13]
	s_andn2_b64 exec, exec, s[14:15]
	s_cbranch_execnz .LBB0_1885

; DI void phase_norm(const Params& p, int mode, int l, int row_lo, int nrows, int bid, int nb) {
;     ...
;         { const int rn = r + nw < nrows ? r + nw : r;
;           const float* srcn = mode == 0 ? xin_row(p, rn) : (const float*)vrow(p, rn);
; #pragma unroll
;           for (int i = 0; i < 8; ++i) vn[i] = *(const f32x4*)(srcn + i * 256 + lane * 4); }
;         if (mode != 0) {
;             float s = 0.f;
; #pragma unroll
;             for (int i = 0; i < 8; ++i) s += v[i][0] + v[i][1] + v[i][2] + v[i][3];
;             s = wave_sum(s); const float mu = s * (1.f / 2048.f);
;             float q = 0.f;
; #pragma unroll
;             for (int i = 0; i < 8; ++i) { const f32x4 d = v[i] - mu; q += d[0] * d[0] + d[1] * d[1] + d[2] * d[2] + d[3] * d[3]; }
;             q = wave_sum(q); const float rs = rsqrtf(q * (1.f / 2048.f) + LN_EPS);
;             if (mode == 1 && lane == 0) { stats[2 * r] = mu; stats[2 * r + 1] = rs; }
.LBB0_2046:
	v_mov_b64_e32 v[64:65], v[24:25]
	v_mov_b64_e32 v[62:63], v[22:23]
	v_mov_b64_e32 v[60:61], v[16:17]
	v_mov_b64_e32 v[52:53], v[4:5]
	v_mov_b64_e32 v[58:59], v[14:15]
	v_mov_b64_e32 v[50:51], v[2:3]
	v_add_f32_e32 v2, v62, v63
	v_add_f32_e32 v2, v64, v2
	v_add_f32_e32 v3, v58, v59
	v_mov_b64_e32 v[56:57], v[8:9]
	v_add_f32_e32 v2, v65, v2
	v_add_f32_e32 v3, v60, v3
	v_mov_b64_e32 v[54:55], v[6:7]
	v_add_f32_e32 v2, 0, v2
	v_add_f32_e32 v3, v61, v3
	v_add_f32_e32 v2, v3, v2
	v_add_f32_e32 v3, v54, v55
	v_add_f32_e32 v3, v56, v3
	v_add_f32_e32 v3, v57, v3
	v_add_f32_e32 v2, v3, v2
	v_add_f32_e32 v3, v50, v51
	v_mov_b64_e32 v[48:49], v[32:33]
	v_mov_b64_e32 v[44:45], v[28:29]
	v_add_f32_e32 v3, v52, v3
	v_mov_b64_e32 v[46:47], v[30:31]
	v_mov_b64_e32 v[42:43], v[26:27]
	v_add_f32_e32 v3, v53, v3
	v_add_f32_e32 v9, v3, v2
	v_mov_b32_e32 v2, v42
	v_mov_b32_e32 v3, v46
	v_mov_b32_e32 v4, v43
	v_mov_b32_e32 v5, v47
	v_pk_add_f32 v[2:3], v[2:3], v[4:5]
	v_mov_b32_e32 v4, v44
	v_mov_b32_e32 v5, v48
	v_pk_add_f32 v[2:3], v[4:5], v[2:3]
	v_mov_b32_e32 v4, v45
	v_mov_b32_e32 v5, v49
	v_mov_b64_e32 v[40:41], v[20:21]
	v_mov_b64_e32 v[36:37], v[12:13]
	v_pk_add_f32 v[2:3], v[4:5], v[2:3]
	v_mov_b64_e32 v[38:39], v[18:19]
	v_mov_b64_e32 v[34:35], v[10:11]
	v_add_f32_e32 v3, v3, v9
	v_add_f32_e32 v9, v2, v3
	v_mov_b32_e32 v2, v34
	v_mov_b32_e32 v3, v38
	v_mov_b32_e32 v4, v35
	v_mov_b32_e32 v5, v39
	v_pk_add_f32 v[2:3], v[2:3], v[4:5]
	v_mov_b32_e32 v4, v36
	v_mov_b32_e32 v5, v40
	v_pk_add_f32 v[2:3], v[4:5], v[2:3]
	v_mov_b32_e32 v4, v37
	v_mov_b32_e32 v5, v41
	v_pk_add_f32 v[2:3], v[4:5], v[2:3]
	v_add_u32_e32 v122, s20, v108
	v_add_f32_e32 v3, v3, v9
	v_add_f32_e32 v4, v2, v3
	v_mov_b32_e32 v5, v4
	s_nop 1
	v_permlane32_swap_b32_e32 v5, v4
	v_cmp_gt_i32_e64 s[4:5], s26, v122
	v_lshlrev_b32_e32 v68, 2, v66
	s_nop 0
	v_cndmask_b32_e64 v6, v108, v122, s[4:5]
	v_ashrrev_i32_e32 v8, 31, v6
	v_cmp_gt_i32_e64 s[4:5], s26, v6
	v_add_u32_e32 v7, 0xffff8000, v6
	s_nop 0
	v_cndmask_b32_e64 v3, 0, v8, s[4:5]
	s_waitcnt lgkmcnt(0)
	v_add_f32_e32 v8, v4, v5
	v_mov_b32_e32 v9, v8
	s_nop 1
	v_permlane16_swap_b32_e32 v9, v8
	v_cndmask_b32_e64 v2, v7, v6, s[4:5]
	v_mov_b32_e32 v6, s28
	v_mov_b32_e32 v7, s9
	v_cndmask_b32_e64 v5, v6, v7, s[4:5]
	v_mov_b32_e32 v4, s27
	v_mov_b32_e32 v6, s8
	v_cndmask_b32_e64 v4, v4, v6, s[4:5]
	s_waitcnt lgkmcnt(0)
	v_add_f32_e32 v6, v8, v9
	s_nop 1
	v_mov_b32_dpp v7, v6 row_ror:8 row_mask:0xf bank_mask:0xf
	v_lshlrev_b64 v[2:3], 13, v[2:3]
	v_lshl_add_u64 v[2:3], v[4:5], 0, v[2:3]
	v_lshl_add_u64 v[10:11], v[2:3], 0, v[68:69]
	v_add_co_u32_e64 v110, s[4:5], s29, v10
	s_waitcnt lgkmcnt(0)
	v_add_f32_e32 v12, v6, v7
	s_nop 1
	v_mov_b32_dpp v13, v12 row_ror:4 row_mask:0xf bank_mask:0xf
	v_addc_co_u32_e64 v111, s[4:5], 0, v11, s[4:5]
	global_load_dwordx4 v[22:25], v[10:11], off
	global_load_dwordx4 v[14:17], v[10:11], off offset:1024
	global_load_dwordx4 v[6:9], v[10:11], off offset:2048
	global_load_dwordx4 v[2:5], v[10:11], off offset:3072
	v_cmp_lt_i32_e64 s[4:5], s21, v122
	s_waitcnt lgkmcnt(0)
	v_add_f32_e32 v12, v12, v13
	s_nop 1
	v_mov_b32_dpp v13, v12 row_ror:2 row_mask:0xf bank_mask:0xf
	s_waitcnt lgkmcnt(0)
	v_add_f32_e32 v91, v12, v13
	global_load_dwordx4 v[30:33], v[110:111], off
	global_load_dwordx4 v[26:29], v[110:111], off offset:1024
	global_load_dwordx4 v[18:21], v[110:111], off offset:2048
	global_load_dwordx4 v[10:13], v[110:111], off offset:3072
	s_nop 1
	v_mov_b32_dpp v95, v91 row_ror:1 row_mask:0xf bank_mask:0xf
	s_waitcnt lgkmcnt(0)
	v_add_f32_e32 v91, v91, v95
	v_fmamk_f32 v63, v91, 0xba000000, v63
	v_fmamk_f32 v59, v91, 0xba000000, v59
	v_fmamk_f32 v114, v91, 0xba000000, v64
	v_fmac_f32_e32 v62, 0xba000000, v91
	v_mul_f32_e32 v64, v63, v63
	v_fmamk_f32 v112, v91, 0xba000000, v60
	v_fmac_f32_e32 v58, 0xba000000, v91
	v_mul_f32_e32 v60, v59, v59
	v_fmac_f32_e32 v64, v62, v62
	v_fmac_f32_e32 v60, v58, v58
	v_fmamk_f32 v115, v91, 0xba000000, v65
	v_fmac_f32_e32 v64, v114, v114
	v_fmamk_f32 v113, v91, 0xba000000, v61
	v_fmac_f32_e32 v60, v112, v112
	v_fmamk_f32 v55, v91, 0xba000000, v55
	v_fmac_f32_e32 v64, v115, v115
	v_fmac_f32_e32 v60, v113, v113
	v_fmamk_f32 v110, v91, 0xba000000, v56
	v_fmac_f32_e32 v54, 0xba000000, v91
	v_mul_f32_e32 v56, v55, v55
	v_fmamk_f32 v51, v91, 0xba000000, v51
	v_add_f32_e32 v60, v64, v60
	v_fmac_f32_e32 v56, v54, v54
	v_fmamk_f32 v64, v91, 0xba000000, v52
	v_fmac_f32_e32 v50, 0xba000000, v91
	v_mul_f32_e32 v52, v51, v51
	v_fmamk_f32 v111, v91, 0xba000000, v57
	v_fmac_f32_e32 v56, v110, v110
	v_fmac_f32_e32 v52, v50, v50
	v_fmac_f32_e32 v56, v111, v111
	v_fmamk_f32 v65, v91, 0xba000000, v53
	v_fmac_f32_e32 v52, v64, v64
	v_add_f32_e32 v56, v56, v60
	v_fmac_f32_e32 v52, v65, v65
	v_fmamk_f32 v61, v91, 0xba000000, v47
	v_fmac_f32_e32 v46, 0xba000000, v91
	v_fmamk_f32 v60, v91, 0xba000000, v43
	v_add_f32_e32 v95, v52, v56
	v_fmamk_f32 v56, v91, 0xba000000, v45
	v_fmamk_f32 v52, v91, 0xba000000, v44
	v_fmac_f32_e32 v42, 0xba000000, v91
	v_mov_b32_e32 v43, v46
	v_pk_mul_f32 v[44:45], v[60:61], v[60:61]
	v_fmamk_f32 v53, v91, 0xba000000, v48
	v_pk_fma_f32 v[44:45], v[42:43], v[42:43], v[44:45]
	v_fmamk_f32 v57, v91, 0xba000000, v49
	v_pk_fma_f32 v[44:45], v[52:53], v[52:53], v[44:45]
	v_fmamk_f32 v49, v91, 0xba000000, v39
	v_pk_fma_f32 v[44:45], v[56:57], v[56:57], v[44:45]
	v_fmac_f32_e32 v38, 0xba000000, v91
	v_add_f32_e32 v43, v45, v95
	v_fmamk_f32 v48, v91, 0xba000000, v35
	v_add_f32_e32 v43, v44, v43
	v_fmamk_f32 v45, v91, 0xba000000, v41
	v_fmamk_f32 v41, v91, 0xba000000, v40
	v_fmamk_f32 v44, v91, 0xba000000, v37
	v_fmamk_f32 v40, v91, 0xba000000, v36
	v_fmac_f32_e32 v34, 0xba000000, v91
	v_mov_b32_e32 v35, v38
	v_pk_mul_f32 v[36:37], v[48:49], v[48:49]
	s_nop 0
	v_pk_fma_f32 v[36:37], v[34:35], v[34:35], v[36:37]
	s_nop 0
	v_pk_fma_f32 v[36:37], v[40:41], v[40:41], v[36:37]
	s_nop 0
	v_pk_fma_f32 v[36:37], v[44:45], v[44:45], v[36:37]
	s_nop 0
	v_add_f32_e32 v35, v37, v43
	v_add_f32_e32 v35, v36, v35
	v_mov_b32_e32 v36, v35
	s_nop 1
	v_permlane32_swap_b32_e32 v36, v35
	s_waitcnt lgkmcnt(0)
	v_add_f32_e32 v35, v35, v36
	v_mov_b32_e32 v36, v35
	s_nop 1
	v_permlane16_swap_b32_e32 v36, v35
	s_waitcnt lgkmcnt(0)
	v_add_f32_e32 v35, v35, v36
	s_nop 1
	v_mov_b32_dpp v36, v35 row_ror:8 row_mask:0xf bank_mask:0xf
	s_waitcnt lgkmcnt(0)
	v_add_f32_e32 v35, v35, v36
	s_nop 1
	v_mov_b32_dpp v36, v35 row_ror:4 row_mask:0xf bank_mask:0xf
	s_waitcnt lgkmcnt(0)
	v_add_f32_e32 v35, v35, v36
	s_nop 1
	v_mov_b32_dpp v36, v35 row_ror:2 row_mask:0xf bank_mask:0xf
	s_waitcnt lgkmcnt(0)
	v_add_f32_e32 v35, v35, v36
	s_nop 1
	v_mov_b32_dpp v36, v35 row_ror:1 row_mask:0xf bank_mask:0xf
	s_waitcnt lgkmcnt(0)
	v_add_f32_e32 v35, v35, v36
	v_fmamk_f32 v35, v35, 0x3a000000, v109
	v_mul_f32_e32 v36, 0x4b800000, v35
	v_cmp_gt_f32_e64 s[6:7], s31, v35
	s_nop 1
	v_cndmask_b32_e64 v35, v35, v36, s[6:7]
	v_rsq_f32_e32 v35, v35
	s_nop 0
	v_mul_f32_e32 v36, 0x45800000, v35
	v_cndmask_b32_e64 v36, v35, v36, s[6:7]
	s_and_saveexec_b64 s[6:7], vcc
	s_cbranch_execz .LBB0_2045
; DI void phase_norm(const Params& p, int mode, int l, int row_lo, int nrows, int bid, int nb) {
;     ...
;             if (mode == 1 && lane == 0) { stats[2 * r] = mu; stats[2 * r + 1] = rs; }
	v_mul_f32_e32 v124, 0x3a000000, v91
	v_ashrrev_i32_e32 v91, 31, v90
	v_lshl_add_u64 v[126:127], v[90:91], 2, s[22:23]
	v_mov_b32_e32 v125, v36
	global_store_dwordx2 v[126:127], v[124:125], off
	s_branch .LBB0_2045

; DI void phase_norm(const Params& p, int mode, int l, int row_lo, int nrows, int bid, int nb) {
;     ...
;     if (row_lo + gw < nrows) { const int r0 = row_lo + gw; const float* src0 = mode == 0 ? xin_row(p, r0) : (const float*)vrow(p, r0);
; #pragma unroll
;         for (int i = 0; i < 8; ++i) vn[i] = *(const f32x4*)(src0 + i * 256 + lane * 4); }
;     for (int r = row_lo + gw; r < nrows; r += nw) {
;         f32x4 v[8];
; #pragma unroll
;         for (int i = 0; i < 8; ++i) v[i] = vn[i];
;         { const int rn = r + nw < nrows ? r + nw : r;
;           const float* srcn = mode == 0 ? xin_row(p, rn) : (const float*)vrow(p, rn);
; #pragma unroll
;           for (int i = 0; i < 8; ++i) vn[i] = *(const f32x4*)(srcn + i * 256 + lane * 4); }
;         if (mode != 0) {
;             float s = 0.f;
; #pragma unroll
;             for (int i = 0; i < 8; ++i) s += v[i][0] + v[i][1] + v[i][2] + v[i][3];
;             s = wave_sum(s); const float mu = s * (1.f / 2048.f);
;             float q = 0.f;
; #pragma unroll
;             for (int i = 0; i < 8; ++i) { const f32x4 d = v[i] - mu; q += d[0] * d[0] + d[1] * d[1] + d[2] * d[2] + d[3] * d[3]; }
;             q = wave_sum(q); const float rs = rsqrtf(q * (1.f / 2048.f) + LN_EPS);
.LBB0_2381:
	v_add_u32_e32 v146, s2, v96
	v_lshl_add_u64 v[138:139], s[4:5], 0, v[98:99]
	v_cmp_gt_i32_e32 vcc, s14, v146
	s_waitcnt vmcnt(0)
	v_add_f32_e32 v151, v28, v29
	v_add_f32_e32 v152, v24, v25
	v_cndmask_b32_e32 v155, v96, v146, vcc
	v_add_co_u32_e32 v162, vcc, s12, v138
	v_mov_b32_e32 v128, v8
	v_mov_b32_e32 v129, v12
	v_mov_b32_e32 v132, v9
	v_mov_b32_e32 v133, v13
	v_mov_b32_e32 v134, v0
	v_mov_b32_e32 v135, v4
	v_mov_b32_e32 v136, v1
	v_mov_b32_e32 v137, v5
	v_add_f32_e32 v151, v30, v151
	v_addc_co_u32_e32 v163, vcc, 0, v139, vcc
	v_add_f32_e32 v153, v20, v21
	v_mov_b32_e32 v124, v10
	v_mov_b32_e32 v125, v14
	v_mov_b32_e32 v130, v2
	v_mov_b32_e32 v131, v6
	v_add_f32_e32 v152, v26, v152
	v_pk_add_f32 v[128:129], v[128:129], v[132:133]
	v_pk_add_f32 v[132:133], v[134:135], v[136:137]
	v_add_u32_e32 v134, 0xffff8000, v155
	v_add_f32_e32 v136, v31, v151
	v_cmp_gt_i32_e32 vcc, s14, v155
	v_add_f32_e32 v154, v16, v17
	v_mov_b32_e32 v122, v11
	v_mov_b32_e32 v123, v15
	v_add_f32_e32 v153, v22, v153
	v_add_f32_e32 v137, v27, v152
	v_pk_add_f32 v[124:125], v[124:125], v[128:129]
	v_pk_add_f32 v[128:129], v[130:131], v[132:133]
	v_cndmask_b32_e32 v130, v134, v155, vcc
	v_add_f32_e32 v134, 0, v136
	v_cmp_lt_i32_e64 s[0:1], s3, v146
	v_add_f32_e32 v154, v18, v154
	v_mov_b32_e32 v96, v146
	v_add_f32_e32 v146, v23, v153
	v_pk_add_f32 v[164:165], v[122:123], v[124:125]
	v_add_f32_e32 v124, v137, v134
	v_mov_b32_e32 v147, s15
	v_mov_b32_e32 v148, s5
	v_add_f32_e32 v151, v19, v154
	v_add_f32_e32 v124, v146, v124
	v_cndmask_b32_e32 v133, v147, v148, vcc
	v_add_f32_e32 v148, v151, v124
	v_mov_b32_e32 v126, v3
	v_mov_b32_e32 v127, v7
	v_add_f32_e32 v165, v165, v148
	v_pk_add_f32 v[166:167], v[126:127], v[128:129]
	v_add_f32_e32 v164, v164, v165
	v_add_f32_e32 v164, v167, v164
	v_add_f32_e32 v164, v166, v164
	v_mov_b32_e32 v165, v164
	s_nop 1
	v_permlane32_swap_b32_e32 v165, v164
	v_ashrrev_i32_e32 v135, 31, v155
	v_mov_b32_e32 v149, s13
	v_mov_b32_e32 v150, s4
	v_cndmask_b32_e32 v131, 0, v135, vcc
	s_waitcnt lgkmcnt(0)
	v_add_f32_e32 v164, v164, v165
	v_mov_b32_e32 v165, v164
	s_nop 1
	v_permlane16_swap_b32_e32 v165, v164
	v_cndmask_b32_e32 v132, v149, v150, vcc
	v_lshlrev_b64 v[122:123], 13, v[130:131]
	v_lshl_add_u64 v[122:123], v[132:133], 0, v[122:123]
	v_lshl_add_u64 v[146:147], v[122:123], 0, v[100:101]
	v_add_co_u32_e32 v158, vcc, s12, v146
	s_waitcnt lgkmcnt(0)
	v_add_f32_e32 v164, v164, v165
	v_addc_co_u32_e32 v159, vcc, 0, v147, vcc
	s_nop 1
	v_mov_b32_dpp v165, v164 row_ror:8 row_mask:0xf bank_mask:0xf
	global_load_dwordx4 v[32:35], v[102:103], off
	global_load_dwordx4 v[36:39], v[102:103], off offset:1024
	global_load_dwordx4 v[44:47], v[104:105], off
	global_load_dwordx4 v[40:43], v[104:105], off offset:1024
	global_load_dwordx4 v[48:51], v[102:103], off offset:2048
	global_load_dwordx4 v[52:55], v[102:103], off offset:3072
	global_load_dwordx4 v[60:63], v[104:105], off offset:2048
	global_load_dwordx4 v[56:59], v[104:105], off offset:3072
	global_load_dwordx4 v[64:67], v[106:107], off
	global_load_dwordx4 v[68:71], v[108:109], off
	global_load_dwordx4 v[72:75], v[110:111], off
	global_load_dwordx4 v[76:79], v[112:113], off
	global_load_dwordx4 v[80:83], v[114:115], off
	global_load_dwordx4 v[84:87], v[116:117], off
	global_load_dwordx4 v[88:91], v[118:119], off
	global_load_dwordx4 v[92:95], v[120:121], off
	global_load_dwordx4 v[122:125], v[146:147], off
	global_load_dwordx4 v[126:129], v[146:147], off offset:1024
	global_load_dwordx4 v[130:133], v[146:147], off offset:2048
	global_load_dwordx4 v[134:137], v[146:147], off offset:3072
	s_nop 0
	global_load_dwordx4 v[146:149], v[158:159], off
	global_load_dwordx4 v[150:153], v[158:159], off offset:1024
	global_load_dwordx4 v[154:157], v[158:159], off offset:2048
	s_nop 0
	global_load_dwordx4 v[158:161], v[158:159], off offset:3072
	v_lshl_add_u64 v[98:99], v[98:99], 0, s[6:7]
	s_waitcnt lgkmcnt(0)
	v_add_f32_e32 v164, v164, v165
	s_nop 1
	v_mov_b32_dpp v165, v164 row_ror:4 row_mask:0xf bank_mask:0xf
	s_or_b64 s[8:9], s[0:1], s[8:9]
	s_waitcnt lgkmcnt(0)
	v_add_f32_e32 v164, v164, v165
	s_nop 1
	v_mov_b32_dpp v165, v164 row_ror:2 row_mask:0xf bank_mask:0xf
	s_waitcnt lgkmcnt(0)
	v_add_f32_e32 v164, v164, v165
	s_nop 1
	v_mov_b32_dpp v165, v164 row_ror:1 row_mask:0xf bank_mask:0xf
	s_waitcnt lgkmcnt(0)
; DI void phase_norm(const Params& p, int mode, int l, int row_lo, int nrows, int bid, int nb) {
;     ...
;             s = wave_sum(s); const float mu = s * (1.f / 2048.f);
;             float q = 0.f;
; #pragma unroll
;             for (int i = 0; i < 8; ++i) { const f32x4 d = v[i] - mu; q += d[0] * d[0] + d[1] * d[1] + d[2] * d[2] + d[3] * d[3]; }
;             q = wave_sum(q); const float rs = rsqrtf(q * (1.f / 2048.f) + LN_EPS);
;             if (mode == 1 && lane == 0) { stats[2 * r] = mu; stats[2 * r + 1] = rs; }
;             const float* lg = p.in[6] + (size_t)l * D; const float* lb = p.in[7] + (size_t)l * D;
; #pragma unroll
;             for (int i = 0; i < 8; ++i) { const f32x4 gg = *(const f32x4*)(lg + i * 256 + lane * 4), bb = *(const f32x4*)(lb + i * 256 + lane * 4); v[i] = (v[i] - mu) * rs * gg + bb; }
;         }
;         if (mode == 2) {
;             float* dst = p.out + (size_t)r * D;
; #pragma unroll
;             for (int i = 0; i < 8; ++i) *(f32x4*)(dst + i * 256 + lane * 4) = v[i];
	v_add_f32_e32 v164, v164, v165
	v_fmac_f32_e32 v29, 0xba000000, v164
	v_fmac_f32_e32 v25, 0xba000000, v164
	v_fmamk_f32 v28, v164, 0xba000000, v28
	v_fmamk_f32 v24, v164, 0xba000000, v24
	v_fmac_f32_e32 v21, 0xba000000, v164
	v_fmamk_f32 v13, v164, 0xba000000, v13
	v_fmamk_f32 v9, v164, 0xba000000, v9
	v_mul_f32_e32 v180, v29, v29
	v_mul_f32_e32 v181, v25, v25
	v_fmamk_f32 v30, v164, 0xba000000, v30
	v_fmamk_f32 v26, v164, 0xba000000, v26
	v_fmamk_f32 v20, v164, 0xba000000, v20
	v_fmac_f32_e32 v17, 0xba000000, v164
	v_fmac_f32_e32 v12, 0xba000000, v164
	v_fmac_f32_e32 v8, 0xba000000, v164
	v_mul_f32_e32 v182, v21, v21
	v_mov_b32_e32 v166, v9
	v_mov_b32_e32 v167, v13
	v_fmac_f32_e32 v180, v28, v28
	v_fmac_f32_e32 v181, v24, v24
	v_fmamk_f32 v31, v164, 0xba000000, v31
	v_fmamk_f32 v27, v164, 0xba000000, v27
	v_fmamk_f32 v23, v164, 0xba000000, v23
	v_fmamk_f32 v22, v164, 0xba000000, v22
	v_fmamk_f32 v19, v164, 0xba000000, v19
	v_fmamk_f32 v18, v164, 0xba000000, v18
	v_fmamk_f32 v16, v164, 0xba000000, v16
	v_fmamk_f32 v15, v164, 0xba000000, v15
	v_fmamk_f32 v14, v164, 0xba000000, v14
	v_fmamk_f32 v11, v164, 0xba000000, v11
	v_fmamk_f32 v10, v164, 0xba000000, v10
	v_fmamk_f32 v7, v164, 0xba000000, v7
	v_fmamk_f32 v6, v164, 0xba000000, v6
	v_fmamk_f32 v5, v164, 0xba000000, v5
	v_fmac_f32_e32 v4, 0xba000000, v164
	v_fmamk_f32 v3, v164, 0xba000000, v3
	v_fmamk_f32 v2, v164, 0xba000000, v2
	v_fmamk_f32 v1, v164, 0xba000000, v1
	v_fmac_f32_e32 v0, 0xba000000, v164
	v_mul_f32_e32 v183, v17, v17
	v_mov_b32_e32 v164, v8
	v_mov_b32_e32 v165, v12
	v_fmac_f32_e32 v182, v20, v20
	v_pk_mul_f32 v[166:167], v[166:167], v[166:167]
	v_fmac_f32_e32 v180, v30, v30
	v_fmac_f32_e32 v181, v26, v26
	v_mov_b32_e32 v168, v10
	v_mov_b32_e32 v169, v14
	v_fmac_f32_e32 v183, v16, v16
	v_fmac_f32_e32 v182, v22, v22
	v_pk_fma_f32 v[164:165], v[164:165], v[164:165], v[166:167]
	v_fmac_f32_e32 v180, v31, v31
	v_fmac_f32_e32 v181, v27, v27
	v_mov_b32_e32 v174, v1
	v_mov_b32_e32 v175, v5
	v_fmac_f32_e32 v183, v18, v18
	v_fmac_f32_e32 v182, v23, v23
	v_pk_fma_f32 v[164:165], v[168:169], v[168:169], v[164:165]
	v_add_f32_e32 v168, v180, v181
	v_mov_b32_e32 v170, v11
	v_mov_b32_e32 v171, v15
	v_mov_b32_e32 v172, v0
	v_mov_b32_e32 v173, v4
	v_pk_mul_f32 v[174:175], v[174:175], v[174:175]
	v_fmac_f32_e32 v183, v19, v19
	v_add_f32_e32 v168, v182, v168
	v_mov_b32_e32 v176, v2
	v_mov_b32_e32 v177, v6
	v_pk_fma_f32 v[166:167], v[172:173], v[172:173], v[174:175]
	v_pk_fma_f32 v[164:165], v[170:171], v[170:171], v[164:165]
	v_add_f32_e32 v168, v183, v168
	v_mov_b32_e32 v178, v3
	v_mov_b32_e32 v179, v7
	v_pk_fma_f32 v[166:167], v[176:177], v[176:177], v[166:167]
	v_add_f32_e32 v165, v165, v168
	v_pk_fma_f32 v[166:167], v[178:179], v[178:179], v[166:167]
	v_add_f32_e32 v164, v164, v165
	v_add_f32_e32 v164, v167, v164
	v_add_f32_e32 v164, v166, v164
	v_mov_b32_e32 v165, v164
	s_nop 1
	v_permlane32_swap_b32_e32 v165, v164
	s_waitcnt lgkmcnt(0)
	v_add_f32_e32 v164, v164, v165
	v_mov_b32_e32 v165, v164
	s_nop 1
	v_permlane16_swap_b32_e32 v165, v164
	s_waitcnt lgkmcnt(0)
	v_add_f32_e32 v164, v164, v165
	s_nop 1
	v_mov_b32_dpp v165, v164 row_ror:8 row_mask:0xf bank_mask:0xf
	s_waitcnt lgkmcnt(0)
	v_add_f32_e32 v164, v164, v165
	s_nop 1
	v_mov_b32_dpp v165, v164 row_ror:4 row_mask:0xf bank_mask:0xf
	s_waitcnt lgkmcnt(0)
	v_add_f32_e32 v164, v164, v165
	s_nop 1
	v_mov_b32_dpp v165, v164 row_ror:2 row_mask:0xf bank_mask:0xf
	s_waitcnt lgkmcnt(0)
	v_add_f32_e32 v164, v164, v165
	s_nop 1
	v_mov_b32_dpp v165, v164 row_ror:1 row_mask:0xf bank_mask:0xf
	s_waitcnt lgkmcnt(0)
	v_add_f32_e32 v164, v164, v165
	v_fmamk_f32 v164, v164, 0x3a000000, v145
	v_mul_f32_e32 v165, 0x4b800000, v164
	v_cmp_gt_f32_e32 vcc, s10, v164
	s_nop 1
	v_cndmask_b32_e32 v164, v164, v165, vcc
	v_rsq_f32_e32 v164, v164
	s_nop 0
	v_mul_f32_e32 v165, 0x45800000, v164
	v_cndmask_b32_e32 v164, v164, v165, vcc
	v_pk_mul_f32 v[166:167], v[28:29], v[164:165] op_sel_hi:[1,0]
	v_pk_mul_f32 v[168:169], v[30:31], v[164:165] op_sel_hi:[1,0]
	v_pk_mul_f32 v[170:171], v[24:25], v[164:165] op_sel_hi:[1,0]
	v_pk_mul_f32 v[172:173], v[26:27], v[164:165] op_sel_hi:[1,0]
	v_pk_mul_f32 v[174:175], v[20:21], v[164:165] op_sel_hi:[1,0]
	v_pk_mul_f32 v[176:177], v[22:23], v[164:165] op_sel_hi:[1,0]
	v_pk_mul_f32 v[178:179], v[16:17], v[164:165] op_sel_hi:[1,0]
	v_pk_mul_f32 v[180:181], v[18:19], v[164:165] op_sel_hi:[1,0]
	v_pk_mul_f32 v[182:183], v[12:13], v[164:165] op_sel_hi:[1,0]
	v_pk_mul_f32 v[184:185], v[14:15], v[164:165] op_sel_hi:[1,0]
	v_pk_mul_f32 v[186:187], v[8:9], v[164:165] op_sel_hi:[1,0]
	v_pk_mul_f32 v[188:189], v[10:11], v[164:165] op_sel_hi:[1,0]
	v_pk_mul_f32 v[190:191], v[4:5], v[164:165] op_sel_hi:[1,0]
	v_pk_mul_f32 v[192:193], v[6:7], v[164:165] op_sel_hi:[1,0]
	v_pk_mul_f32 v[194:195], v[0:1], v[164:165] op_sel_hi:[1,0]
	v_pk_mul_f32 v[164:165], v[2:3], v[164:165] op_sel_hi:[1,0]
	s_waitcnt vmcnt(0)
	v_mov_b64_e32 v[0:1], v[158:159]
	v_mov_b64_e32 v[4:5], v[154:155]
	v_mov_b64_e32 v[8:9], v[150:151]
	v_mov_b64_e32 v[12:13], v[146:147]
	v_mov_b64_e32 v[16:17], v[134:135]
	v_mov_b64_e32 v[20:21], v[130:131]
	v_mov_b64_e32 v[24:25], v[126:127]
	v_mov_b64_e32 v[28:29], v[122:123]
	v_mov_b64_e32 v[2:3], v[160:161]
	v_mov_b64_e32 v[6:7], v[156:157]
	v_mov_b64_e32 v[10:11], v[152:153]
	v_mov_b64_e32 v[14:15], v[148:149]
	v_mov_b64_e32 v[18:19], v[136:137]
	v_mov_b64_e32 v[22:23], v[132:133]
	v_mov_b64_e32 v[26:27], v[128:129]
	v_mov_b64_e32 v[30:31], v[124:125]
	v_pk_fma_f32 v[34:35], v[34:35], v[168:169], v[46:47]
	v_pk_fma_f32 v[32:33], v[32:33], v[166:167], v[44:45]
	v_pk_fma_f32 v[38:39], v[38:39], v[172:173], v[42:43]
	v_pk_fma_f32 v[36:37], v[36:37], v[170:171], v[40:41]
	v_pk_fma_f32 v[42:43], v[50:51], v[176:177], v[62:63]
	v_pk_fma_f32 v[40:41], v[48:49], v[174:175], v[60:61]
	v_pk_fma_f32 v[46:47], v[54:55], v[180:181], v[58:59]
	v_pk_fma_f32 v[44:45], v[52:53], v[178:179], v[56:57]
	v_pk_fma_f32 v[50:51], v[66:67], v[184:185], v[70:71]
	v_pk_fma_f32 v[48:49], v[64:65], v[182:183], v[68:69]
	v_pk_fma_f32 v[54:55], v[74:75], v[188:189], v[78:79]
	v_pk_fma_f32 v[52:53], v[72:73], v[186:187], v[76:77]
	v_pk_fma_f32 v[58:59], v[82:83], v[192:193], v[86:87]
	v_pk_fma_f32 v[56:57], v[80:81], v[190:191], v[84:85]
	v_pk_fma_f32 v[62:63], v[90:91], v[164:165], v[94:95]
	v_pk_fma_f32 v[60:61], v[88:89], v[194:195], v[92:93]
	global_store_dwordx4 v[138:139], v[32:35], off
	global_store_dwordx4 v[138:139], v[36:39], off offset:1024
	global_store_dwordx4 v[138:139], v[40:43], off offset:2048
	global_store_dwordx4 v[138:139], v[44:47], off offset:3072
	global_store_dwordx4 v[162:163], v[48:51], off
	global_store_dwordx4 v[162:163], v[52:55], off offset:1024
	global_store_dwordx4 v[162:163], v[56:59], off offset:2048
	global_store_dwordx4 v[162:163], v[60:63], off offset:3072
	s_andn2_b64 exec, exec, s[8:9]
	s_cbranch_execnz .LBB0_2381
